# K-loops: hipcc's redundant lgkmcnt waits inside the MFMA bursts removed (20 per iteration), on top of the saddr-form LDS-DMA
# speedup vs baseline: 1.0012x; 1.0009x over previous
; #define PG8_STAGE(bufoff, gbase, voff) do { _Pragma("unroll") for (int _i = 0; _i < 2; ++_i) \
;         glds16_asm((const char*)(gbase) + (voff)[_i], ldsb + (unsigned)((bufoff) + _i * 8192)); } while (0)
; #define PG8_LDA(dst, b, h) do { _Pragma("unroll") for (int m = 0; m < 4; ++m) _Pragma("unroll") for (int k = 0; k < 2; ++k) dst[m][k] = *(const PG8_LAS bf16x8*)(lds + PG8_SA(b, h) + aoff + m * 2048 + k * 1024); } while (0)
; #define PG8_LDB(dst, b, h) do { _Pragma("unroll") for (int n = 0; n < 2; ++n) _Pragma("unroll") for (int k = 0; k < 2; ++k) dst[n][k] = *(const PG8_LAS bf16x8*)(lds + PG8_SB(b, h) + boff + n * 2048 + k * 1024); } while (0)
; #define PG8_MMA(ai, bj, At, Bt) do { __builtin_amdgcn_s_setprio(1); _Pragma("unroll") for (int m = 0; m < 4; ++m) _Pragma("unroll") for (int n = 0; n < 2; ++n) _Pragma("unroll") for (int k = 0; k < 2; ++k) \
;         acc[ai][bj][m][n] = __builtin_amdgcn_mfma_f32_16x16x32_bf16(Bt[n][k], At[m][k], acc[ai][bj][m][n], 0, 0, 0); __builtin_amdgcn_s_setprio(0); } while (0)
; #define PG8_WAIT_V(n) asm volatile("s_waitcnt vmcnt(" #n ")" ::: "memory")
; #define PG8_WAIT_L(n) asm volatile("s_waitcnt lgkmcnt(" #n ")" ::: "memory")
; #define PG8_BAR __builtin_amdgcn_s_barrier()
; #define PG8_SCHED __builtin_amdgcn_sched_barrier(0)
; template <class Epi, class Sched, bool ALIGN_EPI = false, bool SP2 = false>
; __device__ __forceinline__ void gemm_phase(PG8_LAS unsigned char* lds, const Gemm g, const Sched& S, const Epi& E, int wave_u) {
;     ...
;             PG8_LDB(B0, 0, 0); PG8_LDB(B1, 0, 1); PG8_SCHED; PG8_LDA(At, 0, 0); PG8_STAGE(PG8_SA(1, 1), a1 + hstep, voffA);
;             PG8_WAIT_V(8); PG8_WAIT_L(0); PG8_BAR; PG8_MMA(0, 0, At, B0); PG8_MMA(0, 1, At, B1); PG8_BAR; PG8_SCHED;
;             PG8_LDA(At, 0, 1); PG8_STAGE(PG8_SB(0, 0), b2, voffB); PG8_STAGE(PG8_SB(0, 1), b2 + hstep, voffB); PG8_STAGE(PG8_SA(0, 0), a2, voffA);
;             PG8_WAIT_V(8); PG8_WAIT_L(0); PG8_BAR; PG8_MMA(1, 0, At, B0); PG8_MMA(1, 1, At, B1); PG8_BAR; PG8_SCHED;
.LBB0_143:
	v_add_u32_e32 v0, 0x10000, v203
	s_waitcnt lgkmcnt(0)
	ds_read_b128 v[134:137], v0
	ds_read_b128 v[138:141], v0 offset:1024
	ds_read_b128 v[142:145], v0 offset:2048
	ds_read_b128 v[146:149], v0 offset:3072
	v_add_u32_e32 v0, 0x14000, v203
	s_add_u32 s1, s88, 0xfffc0080
	ds_read_b128 v[150:153], v0
	ds_read_b128 v[154:157], v0 offset:1024
	ds_read_b128 v[158:161], v0 offset:2048
	ds_read_b128 v[162:165], v0 offset:3072
	s_addc_u32 s46, s89, -1
	s_and_b64 s[44:45], s[44:45], exec
	s_cselect_b32 s56, s90, s1
	s_cselect_b32 s57, s53, s46
	s_cselect_b32 s45, s25, s65
	s_cselect_b32 s44, s91, s64
	s_add_u32 s46, s56, 0x80
	s_addc_u32 s47, s57, 0
	s_add_u32 s48, s44, 0x80
	s_addc_u32 s49, s45, 0
	ds_read_b128 v[166:169], v204
	ds_read_b128 v[182:185], v204 offset:1024
	ds_read_b128 v[186:189], v204 offset:2048
	ds_read_b128 v[206:209], v204 offset:3072
	ds_read_b128 v[210:213], v204 offset:4096
	ds_read_b128 v[224:227], v204 offset:5120
	ds_read_b128 v[228:231], v204 offset:6144
	ds_read_b128 v[232:235], v204 offset:7168
	s_mov_b32 m0, s78
	s_nop 0
	global_load_lds_dwordx4 v170, s[88:89]
	s_mov_b32 m0, s79
	s_nop 0
	global_load_lds_dwordx4 v174, s[88:89]
	s_waitcnt vmcnt(8)
	s_waitcnt lgkmcnt(0)
	s_barrier
	s_setprio 1
	v_mfma_f32_16x16x32_bf16 v[122:125], v[134:137], v[166:169], v[122:125]
	v_mfma_f32_16x16x32_bf16 v[114:117], v[142:145], v[166:169], v[114:117]
	v_mfma_f32_16x16x32_bf16 v[102:105], v[134:137], v[186:189], v[102:105]
	v_mfma_f32_16x16x32_bf16 v[98:101], v[142:145], v[186:189], v[98:101]
	v_mfma_f32_16x16x32_bf16 v[86:89], v[134:137], v[210:213], v[86:89]
	v_mfma_f32_16x16x32_bf16 v[82:85], v[142:145], v[210:213], v[82:85]
	v_mfma_f32_16x16x32_bf16 v[70:73], v[134:137], v[228:231], v[70:73]
	v_mfma_f32_16x16x32_bf16 v[66:69], v[142:145], v[228:231], v[66:69]
	v_mfma_f32_16x16x32_bf16 v[122:125], v[138:141], v[182:185], v[122:125]
	v_mfma_f32_16x16x32_bf16 v[114:117], v[146:149], v[182:185], v[114:117]
	v_mfma_f32_16x16x32_bf16 v[102:105], v[138:141], v[206:209], v[102:105]
	v_mfma_f32_16x16x32_bf16 v[98:101], v[146:149], v[206:209], v[98:101]
	v_mfma_f32_16x16x32_bf16 v[86:89], v[138:141], v[224:227], v[86:89]
	v_mfma_f32_16x16x32_bf16 v[82:85], v[146:149], v[224:227], v[82:85]
	v_mfma_f32_16x16x32_bf16 v[70:73], v[138:141], v[232:235], v[70:73]
	v_mfma_f32_16x16x32_bf16 v[66:69], v[146:149], v[232:235], v[66:69]
	s_setprio 0
	s_setprio 1
	v_mfma_f32_16x16x32_bf16 v[126:129], v[150:153], v[166:169], v[126:129]
	v_mfma_f32_16x16x32_bf16 v[118:121], v[158:161], v[166:169], v[118:121]
	v_mfma_f32_16x16x32_bf16 v[110:113], v[150:153], v[186:189], v[110:113]
	v_mfma_f32_16x16x32_bf16 v[106:109], v[158:161], v[186:189], v[106:109]
	v_mfma_f32_16x16x32_bf16 v[94:97], v[150:153], v[210:213], v[94:97]
	v_mfma_f32_16x16x32_bf16 v[90:93], v[158:161], v[210:213], v[90:93]
	v_mfma_f32_16x16x32_bf16 v[78:81], v[150:153], v[228:231], v[78:81]
	v_mfma_f32_16x16x32_bf16 v[74:77], v[158:161], v[228:231], v[74:77]
	v_mfma_f32_16x16x32_bf16 v[126:129], v[154:157], v[182:185], v[126:129]
	v_mfma_f32_16x16x32_bf16 v[118:121], v[162:165], v[182:185], v[118:121]
	v_mfma_f32_16x16x32_bf16 v[110:113], v[154:157], v[206:209], v[110:113]
	v_mfma_f32_16x16x32_bf16 v[106:109], v[162:165], v[206:209], v[106:109]
	v_mfma_f32_16x16x32_bf16 v[94:97], v[154:157], v[224:227], v[94:97]
	v_mfma_f32_16x16x32_bf16 v[90:93], v[162:165], v[224:227], v[90:93]
	v_mfma_f32_16x16x32_bf16 v[78:81], v[154:157], v[232:235], v[78:81]
	v_mfma_f32_16x16x32_bf16 v[74:77], v[162:165], v[232:235], v[74:77]
	s_setprio 0
	s_barrier
	ds_read_b128 v[166:169], v204 offset:16384
	ds_read_b128 v[182:185], v204 offset:17408
	ds_read_b128 v[186:189], v204 offset:18432
	ds_read_b128 v[206:209], v204 offset:19456
	ds_read_b128 v[210:213], v204 offset:20480
	ds_read_b128 v[224:227], v204 offset:21504
	ds_read_b128 v[228:231], v204 offset:22528
	ds_read_b128 v[232:235], v204 offset:23552
	s_mov_b32 m0, s20
	s_nop 0
	global_load_lds_dwordx4 v172, s[44:45]
	s_add_u32 vcc_lo, s44, 0x40000
	s_mov_b32 m0, s21
	s_nop 0
	global_load_lds_dwordx4 v176, s[44:45]
	s_addc_u32 vcc_hi, s45, 0
	s_mov_b32 m0, s35
	s_nop 0
	global_load_lds_dwordx4 v172, vcc
	s_mov_b32 m0, s40
	s_nop 0
	global_load_lds_dwordx4 v176, vcc
	s_mov_b32 m0, s2
	s_nop 0
	global_load_lds_dwordx4 v170, s[56:57]
	s_mov_b32 m0, s41
	s_nop 0
	global_load_lds_dwordx4 v174, s[56:57]
	s_waitcnt vmcnt(8)
	s_waitcnt lgkmcnt(0)
	s_barrier
	s_setprio 1
	v_mfma_f32_16x16x32_bf16 v[54:57], v[134:137], v[166:169], v[54:57]
	v_mfma_f32_16x16x32_bf16 v[50:53], v[142:145], v[166:169], v[50:53]
	v_mfma_f32_16x16x32_bf16 v[38:41], v[134:137], v[186:189], v[38:41]
	v_mfma_f32_16x16x32_bf16 v[34:37], v[142:145], v[186:189], v[34:37]
	v_mfma_f32_16x16x32_bf16 v[22:25], v[134:137], v[210:213], v[22:25]
	v_mfma_f32_16x16x32_bf16 v[18:21], v[142:145], v[210:213], v[18:21]
	v_mfma_f32_16x16x32_bf16 v[6:9], v[134:137], v[228:231], v[6:9]
	v_mfma_f32_16x16x32_bf16 v[2:5], v[142:145], v[228:231], v[2:5]
	v_mfma_f32_16x16x32_bf16 v[54:57], v[138:141], v[182:185], v[54:57]
	v_mfma_f32_16x16x32_bf16 v[50:53], v[146:149], v[182:185], v[50:53]
	v_mfma_f32_16x16x32_bf16 v[38:41], v[138:141], v[206:209], v[38:41]
	v_mfma_f32_16x16x32_bf16 v[34:37], v[146:149], v[206:209], v[34:37]
	v_mfma_f32_16x16x32_bf16 v[22:25], v[138:141], v[224:227], v[22:25]
	v_mfma_f32_16x16x32_bf16 v[18:21], v[146:149], v[224:227], v[18:21]
	v_mfma_f32_16x16x32_bf16 v[6:9], v[138:141], v[232:235], v[6:9]
	v_mfma_f32_16x16x32_bf16 v[2:5], v[146:149], v[232:235], v[2:5]
	s_setprio 0
	s_setprio 1
	v_mfma_f32_16x16x32_bf16 v[62:65], v[150:153], v[166:169], v[62:65]
	v_mfma_f32_16x16x32_bf16 v[58:61], v[158:161], v[166:169], v[58:61]
	v_mfma_f32_16x16x32_bf16 v[46:49], v[150:153], v[186:189], v[46:49]
	v_mfma_f32_16x16x32_bf16 v[42:45], v[158:161], v[186:189], v[42:45]
	v_mfma_f32_16x16x32_bf16 v[30:33], v[150:153], v[210:213], v[30:33]
	v_mfma_f32_16x16x32_bf16 v[26:29], v[158:161], v[210:213], v[26:29]
	v_mfma_f32_16x16x32_bf16 v[14:17], v[150:153], v[228:231], v[14:17]
	v_mfma_f32_16x16x32_bf16 v[10:13], v[158:161], v[228:231], v[10:13]
	v_mfma_f32_16x16x32_bf16 v[62:65], v[154:157], v[182:185], v[62:65]
	v_mfma_f32_16x16x32_bf16 v[58:61], v[162:165], v[182:185], v[58:61]
	v_mfma_f32_16x16x32_bf16 v[46:49], v[154:157], v[206:209], v[46:49]
	v_mfma_f32_16x16x32_bf16 v[42:45], v[162:165], v[206:209], v[42:45]
	v_mfma_f32_16x16x32_bf16 v[30:33], v[154:157], v[224:227], v[30:33]
	v_mfma_f32_16x16x32_bf16 v[26:29], v[162:165], v[224:227], v[26:29]
	v_mfma_f32_16x16x32_bf16 v[14:17], v[154:157], v[232:235], v[14:17]
	v_mfma_f32_16x16x32_bf16 v[10:13], v[162:165], v[232:235], v[10:13]
	s_setprio 0
	s_barrier
; #define PG8_STAGE(bufoff, gbase, voff) do { _Pragma("unroll") for (int _i = 0; _i < 2; ++_i) \
;         glds16_asm((const char*)(gbase) + (voff)[_i], ldsb + (unsigned)((bufoff) + _i * 8192)); } while (0)
; #define PG8_LDA(dst, b, h) do { _Pragma("unroll") for (int m = 0; m < 4; ++m) _Pragma("unroll") for (int k = 0; k < 2; ++k) dst[m][k] = *(const PG8_LAS bf16x8*)(lds + PG8_SA(b, h) + aoff + m * 2048 + k * 1024); } while (0)
; #define PG8_LDB(dst, b, h) do { _Pragma("unroll") for (int n = 0; n < 2; ++n) _Pragma("unroll") for (int k = 0; k < 2; ++k) dst[n][k] = *(const PG8_LAS bf16x8*)(lds + PG8_SB(b, h) + boff + n * 2048 + k * 1024); } while (0)
; #define PG8_MMA(ai, bj, At, Bt) do { __builtin_amdgcn_s_setprio(1); _Pragma("unroll") for (int m = 0; m < 4; ++m) _Pragma("unroll") for (int n = 0; n < 2; ++n) _Pragma("unroll") for (int k = 0; k < 2; ++k) \
;         acc[ai][bj][m][n] = __builtin_amdgcn_mfma_f32_16x16x32_bf16(Bt[n][k], At[m][k], acc[ai][bj][m][n], 0, 0, 0); __builtin_amdgcn_s_setprio(0); } while (0)
; #define PG8_WAIT_V(n) asm volatile("s_waitcnt vmcnt(" #n ")" ::: "memory")
; #define PG8_WAIT_L(n) asm volatile("s_waitcnt lgkmcnt(" #n ")" ::: "memory")
; #define PG8_BAR __builtin_amdgcn_s_barrier()
; #define PG8_SCHED __builtin_amdgcn_sched_barrier(0)
; template <class Epi, class Sched, bool ALIGN_EPI = false, bool SP2 = false>
; __device__ __forceinline__ void gemm_phase(PG8_LAS unsigned char* lds, const Gemm g, const Sched& S, const Epi& E, int wave_u) {
;     ...
;         for (int t = 0; t < nt; t += 2) {
;     ...
;             PG8_LDB(B0, 1, 0); PG8_LDB(B1, 1, 1); PG8_SCHED; PG8_LDA(At, 1, 0); PG8_STAGE(PG8_SA(0, 1), a2 + hstep, voffA);
;             PG8_WAIT_V(8); PG8_WAIT_L(0); PG8_BAR; PG8_MMA(0, 0, At, B0); PG8_MMA(0, 1, At, B1); PG8_BAR; PG8_SCHED;
;             PG8_LDA(At, 1, 1); PG8_STAGE(PG8_SB(1, 0), b3, voffB); PG8_STAGE(PG8_SB(1, 1), b3 + hstep, voffB); PG8_STAGE(PG8_SA(1, 0), a3, voffA);
;             PG8_WAIT_V(8); PG8_WAIT_L(0); PG8_BAR; PG8_MMA(1, 0, At, B0); PG8_MMA(1, 1, At, B1); PG8_BAR; PG8_SCHED;
	v_add_u32_e32 v0, 0x18000, v203
	ds_read_b128 v[134:137], v0
	ds_read_b128 v[138:141], v0 offset:1024
	ds_read_b128 v[142:145], v0 offset:2048
	ds_read_b128 v[146:149], v0 offset:3072
	v_add_u32_e32 v0, 0x1c000, v203
	ds_read_b128 v[150:153], v0
	ds_read_b128 v[154:157], v0 offset:1024
	ds_read_b128 v[158:161], v0 offset:2048
	ds_read_b128 v[162:165], v0 offset:3072
	ds_read_b128 v[166:169], v204 offset:32768
	ds_read_b128 v[182:185], v204 offset:33792
	ds_read_b128 v[186:189], v204 offset:34816
	ds_read_b128 v[206:209], v204 offset:35840
	ds_read_b128 v[210:213], v204 offset:36864
	ds_read_b128 v[224:227], v204 offset:37888
	ds_read_b128 v[228:231], v204 offset:38912
	ds_read_b128 v[232:235], v204 offset:39936
	s_add_u32 s56, s56, 0x40000
	s_addc_u32 s57, s57, 0
	s_mov_b32 m0, s52
	s_nop 0
	global_load_lds_dwordx4 v170, s[56:57]
	s_mov_b32 m0, s58
	s_nop 0
	global_load_lds_dwordx4 v174, s[56:57]
	s_waitcnt vmcnt(8)
	s_waitcnt lgkmcnt(0)
	s_barrier
	s_setprio 1
	v_mfma_f32_16x16x32_bf16 v[122:125], v[134:137], v[166:169], v[122:125]
	v_mfma_f32_16x16x32_bf16 v[114:117], v[142:145], v[166:169], v[114:117]
	v_mfma_f32_16x16x32_bf16 v[102:105], v[134:137], v[186:189], v[102:105]
	v_mfma_f32_16x16x32_bf16 v[98:101], v[142:145], v[186:189], v[98:101]
	v_mfma_f32_16x16x32_bf16 v[86:89], v[134:137], v[210:213], v[86:89]
	v_mfma_f32_16x16x32_bf16 v[82:85], v[142:145], v[210:213], v[82:85]
	v_mfma_f32_16x16x32_bf16 v[70:73], v[134:137], v[228:231], v[70:73]
	v_mfma_f32_16x16x32_bf16 v[66:69], v[142:145], v[228:231], v[66:69]
	v_mfma_f32_16x16x32_bf16 v[122:125], v[138:141], v[182:185], v[122:125]
	v_mfma_f32_16x16x32_bf16 v[114:117], v[146:149], v[182:185], v[114:117]
	v_mfma_f32_16x16x32_bf16 v[102:105], v[138:141], v[206:209], v[102:105]
	v_mfma_f32_16x16x32_bf16 v[98:101], v[146:149], v[206:209], v[98:101]
	v_mfma_f32_16x16x32_bf16 v[86:89], v[138:141], v[224:227], v[86:89]
	v_mfma_f32_16x16x32_bf16 v[82:85], v[146:149], v[224:227], v[82:85]
	v_mfma_f32_16x16x32_bf16 v[70:73], v[138:141], v[232:235], v[70:73]
	v_mfma_f32_16x16x32_bf16 v[66:69], v[146:149], v[232:235], v[66:69]
	s_setprio 0
	s_setprio 1
	v_mfma_f32_16x16x32_bf16 v[126:129], v[150:153], v[166:169], v[126:129]
	v_mfma_f32_16x16x32_bf16 v[118:121], v[158:161], v[166:169], v[118:121]
	v_mfma_f32_16x16x32_bf16 v[110:113], v[150:153], v[186:189], v[110:113]
	v_mfma_f32_16x16x32_bf16 v[106:109], v[158:161], v[186:189], v[106:109]
	v_mfma_f32_16x16x32_bf16 v[94:97], v[150:153], v[210:213], v[94:97]
	v_mfma_f32_16x16x32_bf16 v[90:93], v[158:161], v[210:213], v[90:93]
	v_mfma_f32_16x16x32_bf16 v[78:81], v[150:153], v[228:231], v[78:81]
	v_mfma_f32_16x16x32_bf16 v[74:77], v[158:161], v[228:231], v[74:77]
	v_mfma_f32_16x16x32_bf16 v[126:129], v[154:157], v[182:185], v[126:129]
	v_mfma_f32_16x16x32_bf16 v[118:121], v[162:165], v[182:185], v[118:121]
	v_mfma_f32_16x16x32_bf16 v[110:113], v[154:157], v[206:209], v[110:113]
	v_mfma_f32_16x16x32_bf16 v[106:109], v[162:165], v[206:209], v[106:109]
	v_mfma_f32_16x16x32_bf16 v[94:97], v[154:157], v[224:227], v[94:97]
	v_mfma_f32_16x16x32_bf16 v[90:93], v[162:165], v[224:227], v[90:93]
	v_mfma_f32_16x16x32_bf16 v[78:81], v[154:157], v[232:235], v[78:81]
	v_mfma_f32_16x16x32_bf16 v[74:77], v[162:165], v[232:235], v[74:77]
	s_setprio 0
	s_barrier
	ds_read_b128 v[166:169], v204 offset:49152
	ds_read_b128 v[182:185], v204 offset:50176
	ds_read_b128 v[186:189], v204 offset:51200
	ds_read_b128 v[206:209], v204 offset:52224
	ds_read_b128 v[210:213], v204 offset:53248
	ds_read_b128 v[224:227], v204 offset:54272
	ds_read_b128 v[228:231], v204 offset:55296
	ds_read_b128 v[232:235], v204 offset:56320
	s_mov_b32 m0, s60
	s_nop 0
	global_load_lds_dwordx4 v172, s[48:49]
	s_add_u32 s44, s44, 0x40080
	s_mov_b32 m0, s61
	s_nop 0
	global_load_lds_dwordx4 v176, s[48:49]
	s_addc_u32 s45, s45, 0
	s_mov_b32 m0, s67
	s_nop 0
	global_load_lds_dwordx4 v172, s[44:45]
	s_mov_b32 m0, s75
	s_nop 0
	global_load_lds_dwordx4 v176, s[44:45]
	s_mov_b32 m0, s63
	s_nop 0
	global_load_lds_dwordx4 v170, s[46:47]
	s_mov_b32 m0, s66
	s_nop 0
	global_load_lds_dwordx4 v174, s[46:47]
	s_waitcnt vmcnt(8)
	s_waitcnt lgkmcnt(0)
	s_barrier
	s_setprio 1
	v_mfma_f32_16x16x32_bf16 v[54:57], v[134:137], v[166:169], v[54:57]
	v_mfma_f32_16x16x32_bf16 v[50:53], v[142:145], v[166:169], v[50:53]
	v_mfma_f32_16x16x32_bf16 v[38:41], v[134:137], v[186:189], v[38:41]
	v_mfma_f32_16x16x32_bf16 v[34:37], v[142:145], v[186:189], v[34:37]
	v_mfma_f32_16x16x32_bf16 v[22:25], v[134:137], v[210:213], v[22:25]
	v_mfma_f32_16x16x32_bf16 v[18:21], v[142:145], v[210:213], v[18:21]
	v_mfma_f32_16x16x32_bf16 v[6:9], v[134:137], v[228:231], v[6:9]
	v_mfma_f32_16x16x32_bf16 v[2:5], v[142:145], v[228:231], v[2:5]
	v_mfma_f32_16x16x32_bf16 v[54:57], v[138:141], v[182:185], v[54:57]
	v_mfma_f32_16x16x32_bf16 v[50:53], v[146:149], v[182:185], v[50:53]
	v_mfma_f32_16x16x32_bf16 v[38:41], v[138:141], v[206:209], v[38:41]
	v_mfma_f32_16x16x32_bf16 v[34:37], v[146:149], v[206:209], v[34:37]
	v_mfma_f32_16x16x32_bf16 v[22:25], v[138:141], v[224:227], v[22:25]
	v_mfma_f32_16x16x32_bf16 v[18:21], v[146:149], v[224:227], v[18:21]
	v_mfma_f32_16x16x32_bf16 v[6:9], v[138:141], v[232:235], v[6:9]
	v_mfma_f32_16x16x32_bf16 v[2:5], v[146:149], v[232:235], v[2:5]
	s_setprio 0
	s_setprio 1
	v_mfma_f32_16x16x32_bf16 v[62:65], v[150:153], v[166:169], v[62:65]
	v_mfma_f32_16x16x32_bf16 v[58:61], v[158:161], v[166:169], v[58:61]
	v_mfma_f32_16x16x32_bf16 v[46:49], v[150:153], v[186:189], v[46:49]
	v_mfma_f32_16x16x32_bf16 v[42:45], v[158:161], v[186:189], v[42:45]
	v_mfma_f32_16x16x32_bf16 v[30:33], v[150:153], v[210:213], v[30:33]
	v_mfma_f32_16x16x32_bf16 v[26:29], v[158:161], v[210:213], v[26:29]
	v_mfma_f32_16x16x32_bf16 v[14:17], v[150:153], v[228:231], v[14:17]
	v_mfma_f32_16x16x32_bf16 v[10:13], v[158:161], v[228:231], v[10:13]
	v_mfma_f32_16x16x32_bf16 v[62:65], v[154:157], v[182:185], v[62:65]
	v_mfma_f32_16x16x32_bf16 v[58:61], v[162:165], v[182:185], v[58:61]
	v_mfma_f32_16x16x32_bf16 v[46:49], v[154:157], v[206:209], v[46:49]
	v_mfma_f32_16x16x32_bf16 v[42:45], v[162:165], v[206:209], v[42:45]
	v_mfma_f32_16x16x32_bf16 v[30:33], v[154:157], v[224:227], v[30:33]
	v_mfma_f32_16x16x32_bf16 v[26:29], v[162:165], v[224:227], v[26:29]
	v_mfma_f32_16x16x32_bf16 v[14:17], v[154:157], v[232:235], v[14:17]
	v_mfma_f32_16x16x32_bf16 v[10:13], v[162:165], v[232:235], v[10:13]
	s_setprio 0
	s_barrier
	s_add_i32 s84, s84, 2
	s_add_u32 s88, s88, 0x100
	s_addc_u32 s89, s89, 0
	s_add_u32 s64, s64, 0x100
	s_addc_u32 s65, s65, 0
	s_cmp_gt_u32 s84, 13
	s_cbranch_scc1 .LBB0_146

; #define PG8_STAGE(bufoff, gbase, voff) do { _Pragma("unroll") for (int _i = 0; _i < 2; ++_i) \
;         glds16_asm((const char*)(gbase) + (voff)[_i], ldsb + (unsigned)((bufoff) + _i * 8192)); } while (0)
; #define PG8_LDA(dst, b, h) do { _Pragma("unroll") for (int m = 0; m < 4; ++m) _Pragma("unroll") for (int k = 0; k < 2; ++k) dst[m][k] = *(const PG8_LAS bf16x8*)(lds + PG8_SA(b, h) + aoff + m * 2048 + k * 1024); } while (0)
; #define PG8_LDB(dst, b, h) do { _Pragma("unroll") for (int n = 0; n < 2; ++n) _Pragma("unroll") for (int k = 0; k < 2; ++k) dst[n][k] = *(const PG8_LAS bf16x8*)(lds + PG8_SB(b, h) + boff + n * 2048 + k * 1024); } while (0)
; #define PG8_MMA(ai, bj, At, Bt) do { __builtin_amdgcn_s_setprio(1); _Pragma("unroll") for (int m = 0; m < 4; ++m) _Pragma("unroll") for (int n = 0; n < 2; ++n) _Pragma("unroll") for (int k = 0; k < 2; ++k) \
;         acc[ai][bj][m][n] = __builtin_amdgcn_mfma_f32_16x16x32_bf16(Bt[n][k], At[m][k], acc[ai][bj][m][n], 0, 0, 0); __builtin_amdgcn_s_setprio(0); } while (0)
; #define PG8_WAIT_V(n) asm volatile("s_waitcnt vmcnt(" #n ")" ::: "memory")
; #define PG8_WAIT_L(n) asm volatile("s_waitcnt lgkmcnt(" #n ")" ::: "memory")
; #define PG8_BAR __builtin_amdgcn_s_barrier()
; #define PG8_SCHED __builtin_amdgcn_sched_barrier(0)
; template <class Epi, class Sched, bool ALIGN_EPI = false, bool SP2 = false>
; __device__ __forceinline__ void gemm_phase(PG8_LAS unsigned char* lds, const Gemm g, const Sched& S, const Epi& E, int wave_u) {
;     ...
;             PG8_LDB(B0, 0, 0); PG8_LDB(B1, 0, 1); PG8_SCHED; PG8_LDA(At, 0, 0); PG8_STAGE(PG8_SA(1, 1), a1 + hstep, voffA);
;             PG8_WAIT_V(8); PG8_WAIT_L(0); PG8_BAR; PG8_MMA(0, 0, At, B0); PG8_MMA(0, 1, At, B1); PG8_BAR; PG8_SCHED;
;             PG8_LDA(At, 0, 1); PG8_STAGE(PG8_SB(0, 0), b2, voffB); PG8_STAGE(PG8_SB(0, 1), b2 + hstep, voffB); PG8_STAGE(PG8_SA(0, 0), a2, voffA);
;             PG8_WAIT_V(8); PG8_WAIT_L(0); PG8_BAR; PG8_MMA(1, 0, At, B0); PG8_MMA(1, 1, At, B1); PG8_BAR; PG8_SCHED;
.LBB0_264:
	v_add_u32_e32 v0, 0x10000, v211
	s_waitcnt lgkmcnt(0)
	ds_read_b128 v[130:133], v0
	ds_read_b128 v[138:141], v0 offset:1024
	ds_read_b128 v[142:145], v0 offset:2048
	ds_read_b128 v[146:149], v0 offset:3072
	v_add_u32_e32 v0, 0x14000, v211
	s_add_u32 s1, s88, 0xfffc0080
	ds_read_b128 v[150:153], v0
	ds_read_b128 v[154:157], v0 offset:1024
	ds_read_b128 v[158:161], v0 offset:2048
	ds_read_b128 v[162:165], v0 offset:3072
	s_addc_u32 s46, s89, -1
	s_and_b64 s[44:45], s[44:45], exec
	s_cselect_b32 s56, s19, s1
	s_cselect_b32 s57, s13, s46
	s_cselect_b32 s45, s17, s41
	s_cselect_b32 s44, s29, s40
	s_add_u32 s46, s56, 0x80
	s_addc_u32 s47, s57, 0
	s_add_u32 s48, s44, 0x80
	s_addc_u32 s49, s45, 0
	ds_read_b128 v[166:169], v212
	ds_read_b128 v[170:173], v212 offset:1024
	ds_read_b128 v[174:177], v212 offset:2048
	ds_read_b128 v[198:201], v212 offset:3072
	ds_read_b128 v[224:227], v212 offset:4096
	ds_read_b128 v[228:231], v212 offset:5120
	ds_read_b128 v[232:235], v212 offset:6144
	ds_read_b128 v[236:239], v212 offset:7168
	s_mov_b32 m0, s27
	s_nop 0
	global_load_lds_dwordx4 v178, s[88:89]
	s_mov_b32 m0, s60
	s_nop 0
	global_load_lds_dwordx4 v182, s[88:89]
	s_waitcnt vmcnt(8)
	s_waitcnt lgkmcnt(0)
	s_barrier
	s_setprio 1
	v_mfma_f32_16x16x32_bf16 v[134:137], v[130:133], v[166:169], v[134:137]
	v_mfma_f32_16x16x32_bf16 v[122:125], v[142:145], v[166:169], v[122:125]
	v_mfma_f32_16x16x32_bf16 v[110:113], v[130:133], v[174:177], v[110:113]
	v_mfma_f32_16x16x32_bf16 v[106:109], v[142:145], v[174:177], v[106:109]
	v_mfma_f32_16x16x32_bf16 v[94:97], v[130:133], v[224:227], v[94:97]
	v_mfma_f32_16x16x32_bf16 v[90:93], v[142:145], v[224:227], v[90:93]
	v_mfma_f32_16x16x32_bf16 v[78:81], v[130:133], v[232:235], v[78:81]
	v_mfma_f32_16x16x32_bf16 v[74:77], v[142:145], v[232:235], v[74:77]
	v_mfma_f32_16x16x32_bf16 v[134:137], v[138:141], v[170:173], v[134:137]
	v_mfma_f32_16x16x32_bf16 v[122:125], v[146:149], v[170:173], v[122:125]
	v_mfma_f32_16x16x32_bf16 v[110:113], v[138:141], v[198:201], v[110:113]
	v_mfma_f32_16x16x32_bf16 v[106:109], v[146:149], v[198:201], v[106:109]
	v_mfma_f32_16x16x32_bf16 v[94:97], v[138:141], v[228:231], v[94:97]
	v_mfma_f32_16x16x32_bf16 v[90:93], v[146:149], v[228:231], v[90:93]
	v_mfma_f32_16x16x32_bf16 v[78:81], v[138:141], v[236:239], v[78:81]
	v_mfma_f32_16x16x32_bf16 v[74:77], v[146:149], v[236:239], v[74:77]
	s_setprio 0
	s_setprio 1
	v_mfma_f32_16x16x32_bf16 v[118:121], v[150:153], v[166:169], v[118:121]
	v_mfma_f32_16x16x32_bf16 v[114:117], v[158:161], v[166:169], v[114:117]
	v_mfma_f32_16x16x32_bf16 v[102:105], v[150:153], v[174:177], v[102:105]
	v_mfma_f32_16x16x32_bf16 v[98:101], v[158:161], v[174:177], v[98:101]
	v_mfma_f32_16x16x32_bf16 v[86:89], v[150:153], v[224:227], v[86:89]
	v_mfma_f32_16x16x32_bf16 v[82:85], v[158:161], v[224:227], v[82:85]
	v_mfma_f32_16x16x32_bf16 v[70:73], v[150:153], v[232:235], v[70:73]
	v_mfma_f32_16x16x32_bf16 v[66:69], v[158:161], v[232:235], v[66:69]
	v_mfma_f32_16x16x32_bf16 v[118:121], v[154:157], v[170:173], v[118:121]
	v_mfma_f32_16x16x32_bf16 v[114:117], v[162:165], v[170:173], v[114:117]
	v_mfma_f32_16x16x32_bf16 v[102:105], v[154:157], v[198:201], v[102:105]
	v_mfma_f32_16x16x32_bf16 v[98:101], v[162:165], v[198:201], v[98:101]
	v_mfma_f32_16x16x32_bf16 v[86:89], v[154:157], v[228:231], v[86:89]
	v_mfma_f32_16x16x32_bf16 v[82:85], v[162:165], v[228:231], v[82:85]
	v_mfma_f32_16x16x32_bf16 v[70:73], v[154:157], v[236:239], v[70:73]
	v_mfma_f32_16x16x32_bf16 v[66:69], v[162:165], v[236:239], v[66:69]
	s_setprio 0
	s_barrier
	ds_read_b128 v[166:169], v212 offset:16384
	ds_read_b128 v[170:173], v212 offset:17408
	ds_read_b128 v[174:177], v212 offset:18432
	ds_read_b128 v[198:201], v212 offset:19456
	ds_read_b128 v[224:227], v212 offset:20480
	ds_read_b128 v[228:231], v212 offset:21504
	ds_read_b128 v[232:235], v212 offset:22528
	ds_read_b128 v[236:239], v212 offset:23552
	s_mov_b32 m0, s63
	s_nop 0
	global_load_lds_dwordx4 v180, s[44:45]
	s_add_u32 s58, s44, 0x40000
	s_mov_b32 m0, s86
	s_nop 0
	global_load_lds_dwordx4 v184, s[44:45]
	s_addc_u32 s59, s45, 0
	s_mov_b32 m0, s87
	s_nop 0
	global_load_lds_dwordx4 v180, s[58:59]
	s_mov_b32 m0, s90
	s_nop 0
	global_load_lds_dwordx4 v184, s[58:59]
	s_mov_b32 m0, s2
	s_nop 0
	global_load_lds_dwordx4 v178, s[56:57]
	s_mov_b32 m0, s91
	s_nop 0
	global_load_lds_dwordx4 v182, s[56:57]
	s_waitcnt vmcnt(8)
	s_waitcnt lgkmcnt(0)
	s_barrier
	s_setprio 1
	v_mfma_f32_16x16x32_bf16 v[62:65], v[130:133], v[166:169], v[62:65]
	v_mfma_f32_16x16x32_bf16 v[58:61], v[142:145], v[166:169], v[58:61]
	v_mfma_f32_16x16x32_bf16 v[46:49], v[130:133], v[174:177], v[46:49]
	v_mfma_f32_16x16x32_bf16 v[42:45], v[142:145], v[174:177], v[42:45]
	v_mfma_f32_16x16x32_bf16 v[30:33], v[130:133], v[224:227], v[30:33]
	v_mfma_f32_16x16x32_bf16 v[26:29], v[142:145], v[224:227], v[26:29]
	v_mfma_f32_16x16x32_bf16 v[14:17], v[130:133], v[232:235], v[14:17]
	v_mfma_f32_16x16x32_bf16 v[10:13], v[142:145], v[232:235], v[10:13]
	v_mfma_f32_16x16x32_bf16 v[62:65], v[138:141], v[170:173], v[62:65]
	v_mfma_f32_16x16x32_bf16 v[58:61], v[146:149], v[170:173], v[58:61]
	v_mfma_f32_16x16x32_bf16 v[46:49], v[138:141], v[198:201], v[46:49]
	v_mfma_f32_16x16x32_bf16 v[42:45], v[146:149], v[198:201], v[42:45]
	v_mfma_f32_16x16x32_bf16 v[30:33], v[138:141], v[228:231], v[30:33]
	v_mfma_f32_16x16x32_bf16 v[26:29], v[146:149], v[228:231], v[26:29]
	v_mfma_f32_16x16x32_bf16 v[14:17], v[138:141], v[236:239], v[14:17]
	v_mfma_f32_16x16x32_bf16 v[10:13], v[146:149], v[236:239], v[10:13]
	s_setprio 0
	s_setprio 1
	v_mfma_f32_16x16x32_bf16 v[54:57], v[150:153], v[166:169], v[54:57]
	v_mfma_f32_16x16x32_bf16 v[50:53], v[158:161], v[166:169], v[50:53]
	v_mfma_f32_16x16x32_bf16 v[38:41], v[150:153], v[174:177], v[38:41]
	v_mfma_f32_16x16x32_bf16 v[34:37], v[158:161], v[174:177], v[34:37]
	v_mfma_f32_16x16x32_bf16 v[22:25], v[150:153], v[224:227], v[22:25]
	v_mfma_f32_16x16x32_bf16 v[18:21], v[158:161], v[224:227], v[18:21]
	v_mfma_f32_16x16x32_bf16 v[6:9], v[150:153], v[232:235], v[6:9]
	v_mfma_f32_16x16x32_bf16 v[2:5], v[158:161], v[232:235], v[2:5]
	v_mfma_f32_16x16x32_bf16 v[54:57], v[154:157], v[170:173], v[54:57]
	v_mfma_f32_16x16x32_bf16 v[50:53], v[162:165], v[170:173], v[50:53]
	v_mfma_f32_16x16x32_bf16 v[38:41], v[154:157], v[198:201], v[38:41]
	v_mfma_f32_16x16x32_bf16 v[34:37], v[162:165], v[198:201], v[34:37]
	v_mfma_f32_16x16x32_bf16 v[22:25], v[154:157], v[228:231], v[22:25]
	v_mfma_f32_16x16x32_bf16 v[18:21], v[162:165], v[228:231], v[18:21]
	v_mfma_f32_16x16x32_bf16 v[6:9], v[154:157], v[236:239], v[6:9]
	v_mfma_f32_16x16x32_bf16 v[2:5], v[162:165], v[236:239], v[2:5]
	s_setprio 0
	s_barrier
; #define PG8_STAGE(bufoff, gbase, voff) do { _Pragma("unroll") for (int _i = 0; _i < 2; ++_i) \
;         glds16_asm((const char*)(gbase) + (voff)[_i], ldsb + (unsigned)((bufoff) + _i * 8192)); } while (0)
; #define PG8_LDA(dst, b, h) do { _Pragma("unroll") for (int m = 0; m < 4; ++m) _Pragma("unroll") for (int k = 0; k < 2; ++k) dst[m][k] = *(const PG8_LAS bf16x8*)(lds + PG8_SA(b, h) + aoff + m * 2048 + k * 1024); } while (0)
; #define PG8_LDB(dst, b, h) do { _Pragma("unroll") for (int n = 0; n < 2; ++n) _Pragma("unroll") for (int k = 0; k < 2; ++k) dst[n][k] = *(const PG8_LAS bf16x8*)(lds + PG8_SB(b, h) + boff + n * 2048 + k * 1024); } while (0)
; #define PG8_MMA(ai, bj, At, Bt) do { __builtin_amdgcn_s_setprio(1); _Pragma("unroll") for (int m = 0; m < 4; ++m) _Pragma("unroll") for (int n = 0; n < 2; ++n) _Pragma("unroll") for (int k = 0; k < 2; ++k) \
;         acc[ai][bj][m][n] = __builtin_amdgcn_mfma_f32_16x16x32_bf16(Bt[n][k], At[m][k], acc[ai][bj][m][n], 0, 0, 0); __builtin_amdgcn_s_setprio(0); } while (0)
; #define PG8_WAIT_V(n) asm volatile("s_waitcnt vmcnt(" #n ")" ::: "memory")
; #define PG8_WAIT_L(n) asm volatile("s_waitcnt lgkmcnt(" #n ")" ::: "memory")
; #define PG8_BAR __builtin_amdgcn_s_barrier()
; #define PG8_SCHED __builtin_amdgcn_sched_barrier(0)
; template <class Epi, class Sched, bool ALIGN_EPI = false, bool SP2 = false>
; __device__ __forceinline__ void gemm_phase(PG8_LAS unsigned char* lds, const Gemm g, const Sched& S, const Epi& E, int wave_u) {
;     ...
;         for (int t = 0; t < nt; t += 2) {
;     ...
;             PG8_LDB(B0, 1, 0); PG8_LDB(B1, 1, 1); PG8_SCHED; PG8_LDA(At, 1, 0); PG8_STAGE(PG8_SA(0, 1), a2 + hstep, voffA);
;             PG8_WAIT_V(8); PG8_WAIT_L(0); PG8_BAR; PG8_MMA(0, 0, At, B0); PG8_MMA(0, 1, At, B1); PG8_BAR; PG8_SCHED;
;             PG8_LDA(At, 1, 1); PG8_STAGE(PG8_SB(1, 0), b3, voffB); PG8_STAGE(PG8_SB(1, 1), b3 + hstep, voffB); PG8_STAGE(PG8_SA(1, 0), a3, voffA);
;             PG8_WAIT_V(8); PG8_WAIT_L(0); PG8_BAR; PG8_MMA(1, 0, At, B0); PG8_MMA(1, 1, At, B1); PG8_BAR; PG8_SCHED;
	v_add_u32_e32 v0, 0x18000, v211
	ds_read_b128 v[130:133], v0
	ds_read_b128 v[138:141], v0 offset:1024
	ds_read_b128 v[142:145], v0 offset:2048
	ds_read_b128 v[146:149], v0 offset:3072
	v_add_u32_e32 v0, 0x1c000, v211
	ds_read_b128 v[150:153], v0
	ds_read_b128 v[154:157], v0 offset:1024
	ds_read_b128 v[158:161], v0 offset:2048
	ds_read_b128 v[162:165], v0 offset:3072
	ds_read_b128 v[166:169], v212 offset:32768
	ds_read_b128 v[170:173], v212 offset:33792
	ds_read_b128 v[174:177], v212 offset:34816
	ds_read_b128 v[198:201], v212 offset:35840
	ds_read_b128 v[224:227], v212 offset:36864
	ds_read_b128 v[228:231], v212 offset:37888
	ds_read_b128 v[232:235], v212 offset:38912
	ds_read_b128 v[236:239], v212 offset:39936
	s_add_u32 s56, s56, 0x40000
	s_addc_u32 s57, s57, 0
	s_mov_b32 m0, s20
	s_nop 0
	global_load_lds_dwordx4 v178, s[56:57]
	s_mov_b32 m0, s21
	s_nop 0
	global_load_lds_dwordx4 v182, s[56:57]
	s_waitcnt vmcnt(8)
	s_waitcnt lgkmcnt(0)
	s_barrier
	s_setprio 1
	v_mfma_f32_16x16x32_bf16 v[134:137], v[130:133], v[166:169], v[134:137]
	v_mfma_f32_16x16x32_bf16 v[122:125], v[142:145], v[166:169], v[122:125]
	v_mfma_f32_16x16x32_bf16 v[110:113], v[130:133], v[174:177], v[110:113]
	v_mfma_f32_16x16x32_bf16 v[106:109], v[142:145], v[174:177], v[106:109]
	v_mfma_f32_16x16x32_bf16 v[94:97], v[130:133], v[224:227], v[94:97]
	v_mfma_f32_16x16x32_bf16 v[90:93], v[142:145], v[224:227], v[90:93]
	v_mfma_f32_16x16x32_bf16 v[78:81], v[130:133], v[232:235], v[78:81]
	v_mfma_f32_16x16x32_bf16 v[74:77], v[142:145], v[232:235], v[74:77]
	v_mfma_f32_16x16x32_bf16 v[134:137], v[138:141], v[170:173], v[134:137]
	v_mfma_f32_16x16x32_bf16 v[122:125], v[146:149], v[170:173], v[122:125]
	v_mfma_f32_16x16x32_bf16 v[110:113], v[138:141], v[198:201], v[110:113]
	v_mfma_f32_16x16x32_bf16 v[106:109], v[146:149], v[198:201], v[106:109]
	v_mfma_f32_16x16x32_bf16 v[94:97], v[138:141], v[228:231], v[94:97]
	v_mfma_f32_16x16x32_bf16 v[90:93], v[146:149], v[228:231], v[90:93]
	v_mfma_f32_16x16x32_bf16 v[78:81], v[138:141], v[236:239], v[78:81]
	v_mfma_f32_16x16x32_bf16 v[74:77], v[146:149], v[236:239], v[74:77]
	s_setprio 0
	s_setprio 1
	v_mfma_f32_16x16x32_bf16 v[118:121], v[150:153], v[166:169], v[118:121]
	v_mfma_f32_16x16x32_bf16 v[114:117], v[158:161], v[166:169], v[114:117]
	v_mfma_f32_16x16x32_bf16 v[102:105], v[150:153], v[174:177], v[102:105]
	v_mfma_f32_16x16x32_bf16 v[98:101], v[158:161], v[174:177], v[98:101]
	v_mfma_f32_16x16x32_bf16 v[86:89], v[150:153], v[224:227], v[86:89]
	v_mfma_f32_16x16x32_bf16 v[82:85], v[158:161], v[224:227], v[82:85]
	v_mfma_f32_16x16x32_bf16 v[70:73], v[150:153], v[232:235], v[70:73]
	v_mfma_f32_16x16x32_bf16 v[66:69], v[158:161], v[232:235], v[66:69]
	v_mfma_f32_16x16x32_bf16 v[118:121], v[154:157], v[170:173], v[118:121]
	v_mfma_f32_16x16x32_bf16 v[114:117], v[162:165], v[170:173], v[114:117]
	v_mfma_f32_16x16x32_bf16 v[102:105], v[154:157], v[198:201], v[102:105]
	v_mfma_f32_16x16x32_bf16 v[98:101], v[162:165], v[198:201], v[98:101]
	v_mfma_f32_16x16x32_bf16 v[86:89], v[154:157], v[228:231], v[86:89]
	v_mfma_f32_16x16x32_bf16 v[82:85], v[162:165], v[228:231], v[82:85]
	v_mfma_f32_16x16x32_bf16 v[70:73], v[154:157], v[236:239], v[70:73]
	v_mfma_f32_16x16x32_bf16 v[66:69], v[162:165], v[236:239], v[66:69]
	s_setprio 0
	s_barrier
	ds_read_b128 v[166:169], v212 offset:49152
	ds_read_b128 v[170:173], v212 offset:50176
	ds_read_b128 v[174:177], v212 offset:51200
	ds_read_b128 v[198:201], v212 offset:52224
	ds_read_b128 v[224:227], v212 offset:53248
	ds_read_b128 v[228:231], v212 offset:54272
	ds_read_b128 v[232:235], v212 offset:55296
	ds_read_b128 v[236:239], v212 offset:56320
	s_mov_b32 m0, s22
	s_nop 0
	global_load_lds_dwordx4 v180, s[48:49]
	s_add_u32 s44, s44, 0x40080
	s_mov_b32 m0, s23
	s_nop 0
	global_load_lds_dwordx4 v184, s[48:49]
	s_addc_u32 s45, s45, 0
	s_mov_b32 m0, s61
	s_nop 0
	global_load_lds_dwordx4 v180, s[44:45]
	s_mov_b32 m0, s26
	s_nop 0
	global_load_lds_dwordx4 v184, s[44:45]
	s_mov_b32 m0, s24
	s_nop 0
	global_load_lds_dwordx4 v178, s[46:47]
	s_mov_b32 m0, s25
	s_nop 0
	global_load_lds_dwordx4 v182, s[46:47]
	s_waitcnt vmcnt(8)
	s_waitcnt lgkmcnt(0)
	s_barrier
	s_setprio 1
	v_mfma_f32_16x16x32_bf16 v[62:65], v[130:133], v[166:169], v[62:65]
	v_mfma_f32_16x16x32_bf16 v[58:61], v[142:145], v[166:169], v[58:61]
	v_mfma_f32_16x16x32_bf16 v[46:49], v[130:133], v[174:177], v[46:49]
	v_mfma_f32_16x16x32_bf16 v[42:45], v[142:145], v[174:177], v[42:45]
	v_mfma_f32_16x16x32_bf16 v[30:33], v[130:133], v[224:227], v[30:33]
	v_mfma_f32_16x16x32_bf16 v[26:29], v[142:145], v[224:227], v[26:29]
	v_mfma_f32_16x16x32_bf16 v[14:17], v[130:133], v[232:235], v[14:17]
	v_mfma_f32_16x16x32_bf16 v[10:13], v[142:145], v[232:235], v[10:13]
	v_mfma_f32_16x16x32_bf16 v[62:65], v[138:141], v[170:173], v[62:65]
	v_mfma_f32_16x16x32_bf16 v[58:61], v[146:149], v[170:173], v[58:61]
	v_mfma_f32_16x16x32_bf16 v[46:49], v[138:141], v[198:201], v[46:49]
	v_mfma_f32_16x16x32_bf16 v[42:45], v[146:149], v[198:201], v[42:45]
	v_mfma_f32_16x16x32_bf16 v[30:33], v[138:141], v[228:231], v[30:33]
	v_mfma_f32_16x16x32_bf16 v[26:29], v[146:149], v[228:231], v[26:29]
	v_mfma_f32_16x16x32_bf16 v[14:17], v[138:141], v[236:239], v[14:17]
	v_mfma_f32_16x16x32_bf16 v[10:13], v[146:149], v[236:239], v[10:13]
	s_setprio 0
	s_setprio 1
	v_mfma_f32_16x16x32_bf16 v[54:57], v[150:153], v[166:169], v[54:57]
	v_mfma_f32_16x16x32_bf16 v[50:53], v[158:161], v[166:169], v[50:53]
	v_mfma_f32_16x16x32_bf16 v[38:41], v[150:153], v[174:177], v[38:41]
	v_mfma_f32_16x16x32_bf16 v[34:37], v[158:161], v[174:177], v[34:37]
	v_mfma_f32_16x16x32_bf16 v[22:25], v[150:153], v[224:227], v[22:25]
	v_mfma_f32_16x16x32_bf16 v[18:21], v[158:161], v[224:227], v[18:21]
	v_mfma_f32_16x16x32_bf16 v[6:9], v[150:153], v[232:235], v[6:9]
	v_mfma_f32_16x16x32_bf16 v[2:5], v[158:161], v[232:235], v[2:5]
	v_mfma_f32_16x16x32_bf16 v[54:57], v[154:157], v[170:173], v[54:57]
	v_mfma_f32_16x16x32_bf16 v[50:53], v[162:165], v[170:173], v[50:53]
	v_mfma_f32_16x16x32_bf16 v[38:41], v[154:157], v[198:201], v[38:41]
	v_mfma_f32_16x16x32_bf16 v[34:37], v[162:165], v[198:201], v[34:37]
	v_mfma_f32_16x16x32_bf16 v[22:25], v[154:157], v[228:231], v[22:25]
	v_mfma_f32_16x16x32_bf16 v[18:21], v[162:165], v[228:231], v[18:21]
	v_mfma_f32_16x16x32_bf16 v[6:9], v[154:157], v[236:239], v[6:9]
	v_mfma_f32_16x16x32_bf16 v[2:5], v[162:165], v[236:239], v[2:5]
	s_setprio 0
	s_barrier
	s_add_i32 s52, s52, 2
	s_add_u32 s88, s88, 0x100
	s_addc_u32 s89, s89, 0
	s_add_u32 s40, s40, 0x100
	s_addc_u32 s41, s41, 0
	s_cmp_gt_u32 s52, 13
	s_cbranch_scc1 .LBB0_267

; #define PG8_STAGE(bufoff, gbase, voff) do { _Pragma("unroll") for (int _i = 0; _i < 2; ++_i) \
;         glds16_asm((const char*)(gbase) + (voff)[_i], ldsb + (unsigned)((bufoff) + _i * 8192)); } while (0)
; #define PG8_LDA(dst, b, h) do { _Pragma("unroll") for (int m = 0; m < 4; ++m) _Pragma("unroll") for (int k = 0; k < 2; ++k) dst[m][k] = *(const PG8_LAS bf16x8*)(lds + PG8_SA(b, h) + aoff + m * 2048 + k * 1024); } while (0)
; #define PG8_LDB(dst, b, h) do { _Pragma("unroll") for (int n = 0; n < 2; ++n) _Pragma("unroll") for (int k = 0; k < 2; ++k) dst[n][k] = *(const PG8_LAS bf16x8*)(lds + PG8_SB(b, h) + boff + n * 2048 + k * 1024); } while (0)
; #define PG8_MMA(ai, bj, At, Bt) do { __builtin_amdgcn_s_setprio(1); _Pragma("unroll") for (int m = 0; m < 4; ++m) _Pragma("unroll") for (int n = 0; n < 2; ++n) _Pragma("unroll") for (int k = 0; k < 2; ++k) \
;         acc[ai][bj][m][n] = __builtin_amdgcn_mfma_f32_16x16x32_bf16(Bt[n][k], At[m][k], acc[ai][bj][m][n], 0, 0, 0); __builtin_amdgcn_s_setprio(0); } while (0)
; #define PG8_WAIT_V(n) asm volatile("s_waitcnt vmcnt(" #n ")" ::: "memory")
; #define PG8_WAIT_L(n) asm volatile("s_waitcnt lgkmcnt(" #n ")" ::: "memory")
; #define PG8_BAR __builtin_amdgcn_s_barrier()
; #define PG8_SCHED __builtin_amdgcn_sched_barrier(0)
; template <class Epi, class Sched, bool ALIGN_EPI = false, bool SP2 = false>
; __device__ __forceinline__ void gemm_phase(PG8_LAS unsigned char* lds, const Gemm g, const Sched& S, const Epi& E, int wave_u) {
;     ...
;             PG8_LDB(B0, 0, 0); PG8_LDB(B1, 0, 1); PG8_SCHED; PG8_LDA(At, 0, 0); PG8_STAGE(PG8_SA(1, 1), a1 + hstep, voffA);
;             PG8_WAIT_V(8); PG8_WAIT_L(0); PG8_BAR; PG8_MMA(0, 0, At, B0); PG8_MMA(0, 1, At, B1); PG8_BAR; PG8_SCHED;
;             PG8_LDA(At, 0, 1); PG8_STAGE(PG8_SB(0, 0), b2, voffB); PG8_STAGE(PG8_SB(0, 1), b2 + hstep, voffB); PG8_STAGE(PG8_SA(0, 0), a2, voffA);
;             PG8_WAIT_V(8); PG8_WAIT_L(0); PG8_BAR; PG8_MMA(1, 0, At, B0); PG8_MMA(1, 1, At, B1); PG8_BAR; PG8_SCHED;
.LBB0_980:
	v_add_u32_e32 v0, 0x10000, v227
	ds_read_b128 v[62:65], v0
	ds_read_b128 v[74:77], v0 offset:1024
	ds_read_b128 v[90:93], v0 offset:2048
	ds_read_b128 v[98:101], v0 offset:3072
	v_add_u32_e32 v0, 0x14000, v227
	s_add_u32 s1, s64, 0xfffc0080
	ds_read_b128 v[114:117], v0
	ds_read_b128 v[122:125], v0 offset:1024
	ds_read_b128 v[138:141], v0 offset:2048
	ds_read_b128 v[146:149], v0 offset:3072
	s_addc_u32 s46, s65, -1
	s_and_b64 s[44:45], s[44:45], exec
	s_cselect_b32 s56, s53, s1
	s_cselect_b32 s57, s52, s46
	s_cselect_b32 s45, s19, s61
	s_cselect_b32 s44, s96, s60
	s_add_u32 s46, s56, 0x80
	s_addc_u32 s47, s57, 0
	s_add_u32 s48, s44, 0x80
	s_addc_u32 s49, s45, 0
	ds_read_b128 v[158:161], v228
	ds_read_b128 v[162:165], v228 offset:1024
	ds_read_b128 v[174:177], v228 offset:2048
	ds_read_b128 v[178:181], v228 offset:3072
	ds_read_b128 v[182:185], v228 offset:4096
	ds_read_b128 v[186:189], v228 offset:5120
	ds_read_b128 v[210:213], v228 offset:6144
	ds_read_b128 v[230:233], v228 offset:7168
	s_mov_b32 m0, s7
	s_nop 0
	global_load_lds_dwordx4 v198, s[64:65]
	s_mov_b32 m0, s75
	s_nop 0
	global_load_lds_dwordx4 v202, s[64:65]
	s_waitcnt vmcnt(8)
	s_waitcnt lgkmcnt(0)
	s_barrier
	s_setprio 1
	v_mfma_f32_16x16x32_bf16 v[170:173], v[62:65], v[158:161], v[170:173]
	v_mfma_f32_16x16x32_bf16 v[166:169], v[90:93], v[158:161], v[166:169]
	v_mfma_f32_16x16x32_bf16 v[142:145], v[62:65], v[174:177], v[142:145]
	v_mfma_f32_16x16x32_bf16 v[134:137], v[90:93], v[174:177], v[134:137]
	v_mfma_f32_16x16x32_bf16 v[118:121], v[62:65], v[182:185], v[118:121]
	v_mfma_f32_16x16x32_bf16 v[110:113], v[90:93], v[182:185], v[110:113]
	v_mfma_f32_16x16x32_bf16 v[94:97], v[62:65], v[210:213], v[94:97]
	v_mfma_f32_16x16x32_bf16 v[86:89], v[90:93], v[210:213], v[86:89]
	v_mfma_f32_16x16x32_bf16 v[170:173], v[74:77], v[162:165], v[170:173]
	v_mfma_f32_16x16x32_bf16 v[166:169], v[98:101], v[162:165], v[166:169]
	v_mfma_f32_16x16x32_bf16 v[142:145], v[74:77], v[178:181], v[142:145]
	v_mfma_f32_16x16x32_bf16 v[134:137], v[98:101], v[178:181], v[134:137]
	v_mfma_f32_16x16x32_bf16 v[118:121], v[74:77], v[186:189], v[118:121]
	v_mfma_f32_16x16x32_bf16 v[110:113], v[98:101], v[186:189], v[110:113]
	v_mfma_f32_16x16x32_bf16 v[94:97], v[74:77], v[230:233], v[94:97]
	v_mfma_f32_16x16x32_bf16 v[86:89], v[98:101], v[230:233], v[86:89]
	s_setprio 0
	s_setprio 1
	v_mfma_f32_16x16x32_bf16 v[154:157], v[114:117], v[158:161], v[154:157]
	v_mfma_f32_16x16x32_bf16 v[150:153], v[138:141], v[158:161], v[150:153]
	v_mfma_f32_16x16x32_bf16 v[130:133], v[114:117], v[174:177], v[130:133]
	v_mfma_f32_16x16x32_bf16 v[126:129], v[138:141], v[174:177], v[126:129]
	v_mfma_f32_16x16x32_bf16 v[106:109], v[114:117], v[182:185], v[106:109]
	v_mfma_f32_16x16x32_bf16 v[102:105], v[138:141], v[182:185], v[102:105]
	v_mfma_f32_16x16x32_bf16 v[82:85], v[114:117], v[210:213], v[82:85]
	v_mfma_f32_16x16x32_bf16 v[78:81], v[138:141], v[210:213], v[78:81]
	v_mfma_f32_16x16x32_bf16 v[154:157], v[122:125], v[162:165], v[154:157]
	v_mfma_f32_16x16x32_bf16 v[150:153], v[146:149], v[162:165], v[150:153]
	v_mfma_f32_16x16x32_bf16 v[130:133], v[122:125], v[178:181], v[130:133]
	v_mfma_f32_16x16x32_bf16 v[126:129], v[146:149], v[178:181], v[126:129]
	v_mfma_f32_16x16x32_bf16 v[106:109], v[122:125], v[186:189], v[106:109]
	v_mfma_f32_16x16x32_bf16 v[102:105], v[146:149], v[186:189], v[102:105]
	v_mfma_f32_16x16x32_bf16 v[82:85], v[122:125], v[230:233], v[82:85]
	v_mfma_f32_16x16x32_bf16 v[78:81], v[146:149], v[230:233], v[78:81]
	s_setprio 0
	s_barrier
	ds_read_b128 v[158:161], v228 offset:16384
	ds_read_b128 v[162:165], v228 offset:17408
	ds_read_b128 v[174:177], v228 offset:18432
	ds_read_b128 v[178:181], v228 offset:19456
	ds_read_b128 v[182:185], v228 offset:20480
	ds_read_b128 v[186:189], v228 offset:21504
	ds_read_b128 v[210:213], v228 offset:22528
	ds_read_b128 v[230:233], v228 offset:23552
	s_mov_b32 m0, s35
	s_nop 0
	global_load_lds_dwordx4 v200, s[44:45]
	s_add_u32 vcc_lo, s44, 0x40000
	s_mov_b32 m0, s62
	s_nop 0
	global_load_lds_dwordx4 v204, s[44:45]
	s_addc_u32 vcc_hi, s45, 0
	s_mov_b32 m0, s63
	s_nop 0
	global_load_lds_dwordx4 v200, vcc
	s_mov_b32 m0, s86
	s_nop 0
	global_load_lds_dwordx4 v204, vcc
	s_mov_b32 m0, s2
	s_nop 0
	global_load_lds_dwordx4 v198, s[56:57]
	s_mov_b32 m0, s87
	s_nop 0
	global_load_lds_dwordx4 v202, s[56:57]
	s_waitcnt vmcnt(8)
	s_waitcnt lgkmcnt(0)
	s_barrier
	s_setprio 1
	v_mfma_f32_16x16x32_bf16 v[70:73], v[62:65], v[158:161], v[70:73]
	v_mfma_f32_16x16x32_bf16 v[66:69], v[90:93], v[158:161], v[66:69]
	v_mfma_f32_16x16x32_bf16 v[46:49], v[62:65], v[174:177], v[46:49]
	v_mfma_f32_16x16x32_bf16 v[42:45], v[90:93], v[174:177], v[42:45]
	v_mfma_f32_16x16x32_bf16 v[30:33], v[62:65], v[182:185], v[30:33]
	v_mfma_f32_16x16x32_bf16 v[26:29], v[90:93], v[182:185], v[26:29]
	v_mfma_f32_16x16x32_bf16 v[14:17], v[62:65], v[210:213], v[14:17]
	v_mfma_f32_16x16x32_bf16 v[10:13], v[90:93], v[210:213], v[10:13]
	v_mfma_f32_16x16x32_bf16 v[70:73], v[74:77], v[162:165], v[70:73]
	v_mfma_f32_16x16x32_bf16 v[66:69], v[98:101], v[162:165], v[66:69]
	v_mfma_f32_16x16x32_bf16 v[46:49], v[74:77], v[178:181], v[46:49]
	v_mfma_f32_16x16x32_bf16 v[42:45], v[98:101], v[178:181], v[42:45]
	v_mfma_f32_16x16x32_bf16 v[30:33], v[74:77], v[186:189], v[30:33]
	v_mfma_f32_16x16x32_bf16 v[26:29], v[98:101], v[186:189], v[26:29]
	v_mfma_f32_16x16x32_bf16 v[14:17], v[74:77], v[230:233], v[14:17]
	v_mfma_f32_16x16x32_bf16 v[10:13], v[98:101], v[230:233], v[10:13]
	s_setprio 0
	s_setprio 1
	v_mfma_f32_16x16x32_bf16 v[58:61], v[114:117], v[158:161], v[58:61]
	v_mfma_f32_16x16x32_bf16 v[54:57], v[138:141], v[158:161], v[54:57]
	v_mfma_f32_16x16x32_bf16 v[38:41], v[114:117], v[174:177], v[38:41]
	v_mfma_f32_16x16x32_bf16 v[34:37], v[138:141], v[174:177], v[34:37]
	v_mfma_f32_16x16x32_bf16 v[22:25], v[114:117], v[182:185], v[22:25]
	v_mfma_f32_16x16x32_bf16 v[18:21], v[138:141], v[182:185], v[18:21]
	v_mfma_f32_16x16x32_bf16 v[6:9], v[114:117], v[210:213], v[6:9]
	v_mfma_f32_16x16x32_bf16 v[2:5], v[138:141], v[210:213], v[2:5]
	v_mfma_f32_16x16x32_bf16 v[58:61], v[122:125], v[162:165], v[58:61]
	v_mfma_f32_16x16x32_bf16 v[54:57], v[146:149], v[162:165], v[54:57]
	v_mfma_f32_16x16x32_bf16 v[38:41], v[122:125], v[178:181], v[38:41]
	v_mfma_f32_16x16x32_bf16 v[34:37], v[146:149], v[178:181], v[34:37]
	v_mfma_f32_16x16x32_bf16 v[22:25], v[122:125], v[186:189], v[22:25]
	v_mfma_f32_16x16x32_bf16 v[18:21], v[146:149], v[186:189], v[18:21]
	v_mfma_f32_16x16x32_bf16 v[6:9], v[122:125], v[230:233], v[6:9]
	v_mfma_f32_16x16x32_bf16 v[2:5], v[146:149], v[230:233], v[2:5]
	s_setprio 0
	s_barrier
; #define PG8_STAGE(bufoff, gbase, voff) do { _Pragma("unroll") for (int _i = 0; _i < 2; ++_i) \
;         glds16_asm((const char*)(gbase) + (voff)[_i], ldsb + (unsigned)((bufoff) + _i * 8192)); } while (0)
; #define PG8_LDA(dst, b, h) do { _Pragma("unroll") for (int m = 0; m < 4; ++m) _Pragma("unroll") for (int k = 0; k < 2; ++k) dst[m][k] = *(const PG8_LAS bf16x8*)(lds + PG8_SA(b, h) + aoff + m * 2048 + k * 1024); } while (0)
; #define PG8_LDB(dst, b, h) do { _Pragma("unroll") for (int n = 0; n < 2; ++n) _Pragma("unroll") for (int k = 0; k < 2; ++k) dst[n][k] = *(const PG8_LAS bf16x8*)(lds + PG8_SB(b, h) + boff + n * 2048 + k * 1024); } while (0)
; #define PG8_MMA(ai, bj, At, Bt) do { __builtin_amdgcn_s_setprio(1); _Pragma("unroll") for (int m = 0; m < 4; ++m) _Pragma("unroll") for (int n = 0; n < 2; ++n) _Pragma("unroll") for (int k = 0; k < 2; ++k) \
;         acc[ai][bj][m][n] = __builtin_amdgcn_mfma_f32_16x16x32_bf16(Bt[n][k], At[m][k], acc[ai][bj][m][n], 0, 0, 0); __builtin_amdgcn_s_setprio(0); } while (0)
; #define PG8_WAIT_V(n) asm volatile("s_waitcnt vmcnt(" #n ")" ::: "memory")
; #define PG8_WAIT_L(n) asm volatile("s_waitcnt lgkmcnt(" #n ")" ::: "memory")
; #define PG8_BAR __builtin_amdgcn_s_barrier()
; #define PG8_SCHED __builtin_amdgcn_sched_barrier(0)
; template <class Epi, class Sched, bool ALIGN_EPI = false, bool SP2 = false>
; __device__ __forceinline__ void gemm_phase(PG8_LAS unsigned char* lds, const Gemm g, const Sched& S, const Epi& E, int wave_u) {
;     ...
;         for (int t = 0; t < nt; t += 2) {
;     ...
;             PG8_LDB(B0, 1, 0); PG8_LDB(B1, 1, 1); PG8_SCHED; PG8_LDA(At, 1, 0); PG8_STAGE(PG8_SA(0, 1), a2 + hstep, voffA);
;             PG8_WAIT_V(8); PG8_WAIT_L(0); PG8_BAR; PG8_MMA(0, 0, At, B0); PG8_MMA(0, 1, At, B1); PG8_BAR; PG8_SCHED;
;             PG8_LDA(At, 1, 1); PG8_STAGE(PG8_SB(1, 0), b3, voffB); PG8_STAGE(PG8_SB(1, 1), b3 + hstep, voffB); PG8_STAGE(PG8_SA(1, 0), a3, voffA);
;             PG8_WAIT_V(8); PG8_WAIT_L(0); PG8_BAR; PG8_MMA(1, 0, At, B0); PG8_MMA(1, 1, At, B1); PG8_BAR; PG8_SCHED;
	v_add_u32_e32 v0, 0x18000, v227
	ds_read_b128 v[62:65], v0
	ds_read_b128 v[74:77], v0 offset:1024
	ds_read_b128 v[90:93], v0 offset:2048
	ds_read_b128 v[98:101], v0 offset:3072
	v_add_u32_e32 v0, 0x1c000, v227
	ds_read_b128 v[114:117], v0
	ds_read_b128 v[122:125], v0 offset:1024
	ds_read_b128 v[138:141], v0 offset:2048
	ds_read_b128 v[146:149], v0 offset:3072
	ds_read_b128 v[158:161], v228 offset:32768
	ds_read_b128 v[162:165], v228 offset:33792
	ds_read_b128 v[174:177], v228 offset:34816
	ds_read_b128 v[178:181], v228 offset:35840
	ds_read_b128 v[182:185], v228 offset:36864
	ds_read_b128 v[186:189], v228 offset:37888
	ds_read_b128 v[210:213], v228 offset:38912
	ds_read_b128 v[230:233], v228 offset:39936
	s_add_u32 s56, s56, 0x40000
	s_addc_u32 s57, s57, 0
	s_mov_b32 m0, s88
	s_nop 0
	global_load_lds_dwordx4 v198, s[56:57]
	s_mov_b32 m0, s89
	s_nop 0
	global_load_lds_dwordx4 v202, s[56:57]
	s_waitcnt vmcnt(8)
	s_waitcnt lgkmcnt(0)
	s_barrier
	s_setprio 1
	v_mfma_f32_16x16x32_bf16 v[170:173], v[62:65], v[158:161], v[170:173]
	v_mfma_f32_16x16x32_bf16 v[166:169], v[90:93], v[158:161], v[166:169]
	v_mfma_f32_16x16x32_bf16 v[142:145], v[62:65], v[174:177], v[142:145]
	v_mfma_f32_16x16x32_bf16 v[134:137], v[90:93], v[174:177], v[134:137]
	v_mfma_f32_16x16x32_bf16 v[118:121], v[62:65], v[182:185], v[118:121]
	v_mfma_f32_16x16x32_bf16 v[110:113], v[90:93], v[182:185], v[110:113]
	v_mfma_f32_16x16x32_bf16 v[94:97], v[62:65], v[210:213], v[94:97]
	v_mfma_f32_16x16x32_bf16 v[86:89], v[90:93], v[210:213], v[86:89]
	v_mfma_f32_16x16x32_bf16 v[170:173], v[74:77], v[162:165], v[170:173]
	v_mfma_f32_16x16x32_bf16 v[166:169], v[98:101], v[162:165], v[166:169]
	v_mfma_f32_16x16x32_bf16 v[142:145], v[74:77], v[178:181], v[142:145]
	v_mfma_f32_16x16x32_bf16 v[134:137], v[98:101], v[178:181], v[134:137]
	v_mfma_f32_16x16x32_bf16 v[118:121], v[74:77], v[186:189], v[118:121]
	v_mfma_f32_16x16x32_bf16 v[110:113], v[98:101], v[186:189], v[110:113]
	v_mfma_f32_16x16x32_bf16 v[94:97], v[74:77], v[230:233], v[94:97]
	v_mfma_f32_16x16x32_bf16 v[86:89], v[98:101], v[230:233], v[86:89]
	s_setprio 0
	s_setprio 1
	v_mfma_f32_16x16x32_bf16 v[154:157], v[114:117], v[158:161], v[154:157]
	v_mfma_f32_16x16x32_bf16 v[150:153], v[138:141], v[158:161], v[150:153]
	v_mfma_f32_16x16x32_bf16 v[130:133], v[114:117], v[174:177], v[130:133]
	v_mfma_f32_16x16x32_bf16 v[126:129], v[138:141], v[174:177], v[126:129]
	v_mfma_f32_16x16x32_bf16 v[106:109], v[114:117], v[182:185], v[106:109]
	v_mfma_f32_16x16x32_bf16 v[102:105], v[138:141], v[182:185], v[102:105]
	v_mfma_f32_16x16x32_bf16 v[82:85], v[114:117], v[210:213], v[82:85]
	v_mfma_f32_16x16x32_bf16 v[78:81], v[138:141], v[210:213], v[78:81]
	v_mfma_f32_16x16x32_bf16 v[154:157], v[122:125], v[162:165], v[154:157]
	v_mfma_f32_16x16x32_bf16 v[150:153], v[146:149], v[162:165], v[150:153]
	v_mfma_f32_16x16x32_bf16 v[130:133], v[122:125], v[178:181], v[130:133]
	v_mfma_f32_16x16x32_bf16 v[126:129], v[146:149], v[178:181], v[126:129]
	v_mfma_f32_16x16x32_bf16 v[106:109], v[122:125], v[186:189], v[106:109]
	v_mfma_f32_16x16x32_bf16 v[102:105], v[146:149], v[186:189], v[102:105]
	v_mfma_f32_16x16x32_bf16 v[82:85], v[122:125], v[230:233], v[82:85]
	v_mfma_f32_16x16x32_bf16 v[78:81], v[146:149], v[230:233], v[78:81]
	s_setprio 0
	s_barrier
	ds_read_b128 v[158:161], v228 offset:49152
	ds_read_b128 v[162:165], v228 offset:50176
	ds_read_b128 v[174:177], v228 offset:51200
	ds_read_b128 v[178:181], v228 offset:52224
	ds_read_b128 v[182:185], v228 offset:53248
	ds_read_b128 v[186:189], v228 offset:54272
	ds_read_b128 v[210:213], v228 offset:55296
	ds_read_b128 v[230:233], v228 offset:56320
	s_mov_b32 m0, s90
	s_nop 0
	global_load_lds_dwordx4 v200, s[48:49]
	s_add_u32 s44, s44, 0x40080
	s_mov_b32 m0, s91
	s_nop 0
	global_load_lds_dwordx4 v204, s[48:49]
	s_addc_u32 s45, s45, 0
	s_mov_b32 m0, s66
	s_nop 0
	global_load_lds_dwordx4 v200, s[44:45]
	s_mov_b32 m0, s67
	s_nop 0
	global_load_lds_dwordx4 v204, s[44:45]
	s_mov_b32 m0, s40
	s_nop 0
	global_load_lds_dwordx4 v198, s[46:47]
	s_mov_b32 m0, s41
	s_nop 0
	global_load_lds_dwordx4 v202, s[46:47]
	s_waitcnt vmcnt(8)
	s_waitcnt lgkmcnt(0)
	s_barrier
	s_setprio 1
	v_mfma_f32_16x16x32_bf16 v[70:73], v[62:65], v[158:161], v[70:73]
	v_mfma_f32_16x16x32_bf16 v[66:69], v[90:93], v[158:161], v[66:69]
	v_mfma_f32_16x16x32_bf16 v[46:49], v[62:65], v[174:177], v[46:49]
	v_mfma_f32_16x16x32_bf16 v[42:45], v[90:93], v[174:177], v[42:45]
	v_mfma_f32_16x16x32_bf16 v[30:33], v[62:65], v[182:185], v[30:33]
	v_mfma_f32_16x16x32_bf16 v[26:29], v[90:93], v[182:185], v[26:29]
	v_mfma_f32_16x16x32_bf16 v[14:17], v[62:65], v[210:213], v[14:17]
	v_mfma_f32_16x16x32_bf16 v[10:13], v[90:93], v[210:213], v[10:13]
	v_mfma_f32_16x16x32_bf16 v[70:73], v[74:77], v[162:165], v[70:73]
	v_mfma_f32_16x16x32_bf16 v[66:69], v[98:101], v[162:165], v[66:69]
	v_mfma_f32_16x16x32_bf16 v[46:49], v[74:77], v[178:181], v[46:49]
	v_mfma_f32_16x16x32_bf16 v[42:45], v[98:101], v[178:181], v[42:45]
	v_mfma_f32_16x16x32_bf16 v[30:33], v[74:77], v[186:189], v[30:33]
	v_mfma_f32_16x16x32_bf16 v[26:29], v[98:101], v[186:189], v[26:29]
	v_mfma_f32_16x16x32_bf16 v[14:17], v[74:77], v[230:233], v[14:17]
	v_mfma_f32_16x16x32_bf16 v[10:13], v[98:101], v[230:233], v[10:13]
	s_setprio 0
	s_setprio 1
	v_mfma_f32_16x16x32_bf16 v[58:61], v[114:117], v[158:161], v[58:61]
	v_mfma_f32_16x16x32_bf16 v[54:57], v[138:141], v[158:161], v[54:57]
	v_mfma_f32_16x16x32_bf16 v[38:41], v[114:117], v[174:177], v[38:41]
	v_mfma_f32_16x16x32_bf16 v[34:37], v[138:141], v[174:177], v[34:37]
	v_mfma_f32_16x16x32_bf16 v[22:25], v[114:117], v[182:185], v[22:25]
	v_mfma_f32_16x16x32_bf16 v[18:21], v[138:141], v[182:185], v[18:21]
	v_mfma_f32_16x16x32_bf16 v[6:9], v[114:117], v[210:213], v[6:9]
	v_mfma_f32_16x16x32_bf16 v[2:5], v[138:141], v[210:213], v[2:5]
	v_mfma_f32_16x16x32_bf16 v[58:61], v[122:125], v[162:165], v[58:61]
	v_mfma_f32_16x16x32_bf16 v[54:57], v[146:149], v[162:165], v[54:57]
	v_mfma_f32_16x16x32_bf16 v[38:41], v[122:125], v[178:181], v[38:41]
	v_mfma_f32_16x16x32_bf16 v[34:37], v[146:149], v[178:181], v[34:37]
	v_mfma_f32_16x16x32_bf16 v[22:25], v[122:125], v[186:189], v[22:25]
	v_mfma_f32_16x16x32_bf16 v[18:21], v[146:149], v[186:189], v[18:21]
	v_mfma_f32_16x16x32_bf16 v[6:9], v[122:125], v[230:233], v[6:9]
	v_mfma_f32_16x16x32_bf16 v[2:5], v[146:149], v[230:233], v[2:5]
	s_setprio 0
	s_barrier
	s_add_i32 s84, s84, 2
	s_add_u32 s64, s64, 0x100
	s_addc_u32 s65, s65, 0
	s_add_u32 s60, s60, 0x100
	s_addc_u32 s61, s61, 0
	s_cmp_gt_u32 s84, 13
	s_cbranch_scc1 .LBB0_983

; #define PG8_STAGE(bufoff, gbase, voff) do { _Pragma("unroll") for (int _i = 0; _i < 2; ++_i) \
;         glds16_asm((const char*)(gbase) + (voff)[_i], ldsb + (unsigned)((bufoff) + _i * 8192)); } while (0)
; #define PG8_LDA(dst, b, h) do { _Pragma("unroll") for (int m = 0; m < 4; ++m) _Pragma("unroll") for (int k = 0; k < 2; ++k) dst[m][k] = *(const PG8_LAS bf16x8*)(lds + PG8_SA(b, h) + aoff + m * 2048 + k * 1024); } while (0)
; #define PG8_LDB(dst, b, h) do { _Pragma("unroll") for (int n = 0; n < 2; ++n) _Pragma("unroll") for (int k = 0; k < 2; ++k) dst[n][k] = *(const PG8_LAS bf16x8*)(lds + PG8_SB(b, h) + boff + n * 2048 + k * 1024); } while (0)
; #define PG8_MMA(ai, bj, At, Bt) do { __builtin_amdgcn_s_setprio(1); _Pragma("unroll") for (int m = 0; m < 4; ++m) _Pragma("unroll") for (int n = 0; n < 2; ++n) _Pragma("unroll") for (int k = 0; k < 2; ++k) \
;         acc[ai][bj][m][n] = __builtin_amdgcn_mfma_f32_16x16x32_bf16(Bt[n][k], At[m][k], acc[ai][bj][m][n], 0, 0, 0); __builtin_amdgcn_s_setprio(0); } while (0)
; #define PG8_WAIT_V(n) asm volatile("s_waitcnt vmcnt(" #n ")" ::: "memory")
; #define PG8_WAIT_L(n) asm volatile("s_waitcnt lgkmcnt(" #n ")" ::: "memory")
; #define PG8_BAR __builtin_amdgcn_s_barrier()
; #define PG8_SCHED __builtin_amdgcn_sched_barrier(0)
; template <class Epi, class Sched, bool ALIGN_EPI = false, bool SP2 = false>
; __device__ __forceinline__ void gemm_phase(PG8_LAS unsigned char* lds, const Gemm g, const Sched& S, const Epi& E, int wave_u) {
;     ...
;             PG8_LDB(B0, 0, 0); PG8_LDB(B1, 0, 1); PG8_SCHED; PG8_LDA(At, 0, 0); PG8_STAGE(PG8_SA(1, 1), a1 + hstep, voffA);
;             PG8_WAIT_V(8); PG8_WAIT_L(0); PG8_BAR; PG8_MMA(0, 0, At, B0); PG8_MMA(0, 1, At, B1); PG8_BAR; PG8_SCHED;
;             PG8_LDA(At, 0, 1); PG8_STAGE(PG8_SB(0, 0), b2, voffB); PG8_STAGE(PG8_SB(0, 1), b2 + hstep, voffB); PG8_STAGE(PG8_SA(0, 0), a2, voffA);
;             PG8_WAIT_V(8); PG8_WAIT_L(0); PG8_BAR; PG8_MMA(1, 0, At, B0); PG8_MMA(1, 1, At, B1); PG8_BAR; PG8_SCHED;
.LBB0_1175:
	v_add_u32_e32 v146, 0x10000, v177
	v_add_u32_e32 v179, 0x14000, v177
	s_add_u32 s44, s60, 0xfffc0080
	ds_read_b128 v[134:137], v146
	ds_read_b128 v[138:141], v146 offset:1024
	ds_read_b128 v[142:145], v146 offset:2048
	ds_read_b128 v[146:149], v146 offset:3072
	ds_read_b128 v[150:153], v179
	ds_read_b128 v[154:157], v179 offset:1024
	ds_read_b128 v[158:161], v179 offset:2048
	ds_read_b128 v[180:183], v179 offset:3072
	s_addc_u32 s45, s61, -1
	s_and_b64 s[34:35], s[34:35], exec
	s_cselect_b32 s48, s91, s44
	s_cselect_b32 s49, s90, s45
	s_cselect_b32 s35, s21, s85
	s_cselect_b32 s34, s96, s84
	s_add_u32 s44, s48, 0x80
	s_addc_u32 s45, s49, 0
	s_add_u32 s46, s34, 0x80
	s_addc_u32 s47, s35, 0
	ds_read_b128 v[184:187], v178
	ds_read_b128 v[198:201], v178 offset:1024
	ds_read_b128 v[202:205], v178 offset:2048
	ds_read_b128 v[206:209], v178 offset:3072
	ds_read_b128 v[210:213], v178 offset:4096
	ds_read_b128 v[224:227], v178 offset:5120
	ds_read_b128 v[228:231], v178 offset:6144
	ds_read_b128 v[232:235], v178 offset:7168
	s_mov_b32 m0, s87
	s_nop 0
	global_load_lds_dwordx4 v168, s[60:61]
	s_mov_b32 m0, s88
	s_nop 0
	global_load_lds_dwordx4 v164, s[60:61]
	s_waitcnt vmcnt(8)
	s_waitcnt lgkmcnt(0)
	s_barrier
	s_setprio 1
	v_mfma_f32_16x16x32_bf16 v[122:125], v[134:137], v[184:187], v[122:125]
	v_mfma_f32_16x16x32_bf16 v[114:117], v[142:145], v[184:187], v[114:117]
	v_mfma_f32_16x16x32_bf16 v[106:109], v[134:137], v[202:205], v[106:109]
	v_mfma_f32_16x16x32_bf16 v[98:101], v[142:145], v[202:205], v[98:101]
	v_mfma_f32_16x16x32_bf16 v[90:93], v[134:137], v[210:213], v[90:93]
	v_mfma_f32_16x16x32_bf16 v[82:85], v[142:145], v[210:213], v[82:85]
	v_mfma_f32_16x16x32_bf16 v[74:77], v[134:137], v[228:231], v[74:77]
	v_mfma_f32_16x16x32_bf16 v[66:69], v[142:145], v[228:231], v[66:69]
	v_mfma_f32_16x16x32_bf16 v[122:125], v[138:141], v[198:201], v[122:125]
	v_mfma_f32_16x16x32_bf16 v[114:117], v[146:149], v[198:201], v[114:117]
	v_mfma_f32_16x16x32_bf16 v[106:109], v[138:141], v[206:209], v[106:109]
	v_mfma_f32_16x16x32_bf16 v[98:101], v[146:149], v[206:209], v[98:101]
	v_mfma_f32_16x16x32_bf16 v[90:93], v[138:141], v[224:227], v[90:93]
	v_mfma_f32_16x16x32_bf16 v[82:85], v[146:149], v[224:227], v[82:85]
	v_mfma_f32_16x16x32_bf16 v[74:77], v[138:141], v[232:235], v[74:77]
	v_mfma_f32_16x16x32_bf16 v[66:69], v[146:149], v[232:235], v[66:69]
	s_setprio 0
	s_setprio 1
	v_mfma_f32_16x16x32_bf16 v[126:129], v[150:153], v[184:187], v[126:129]
	v_mfma_f32_16x16x32_bf16 v[118:121], v[158:161], v[184:187], v[118:121]
	v_mfma_f32_16x16x32_bf16 v[110:113], v[150:153], v[202:205], v[110:113]
	v_mfma_f32_16x16x32_bf16 v[102:105], v[158:161], v[202:205], v[102:105]
	v_mfma_f32_16x16x32_bf16 v[94:97], v[150:153], v[210:213], v[94:97]
	v_mfma_f32_16x16x32_bf16 v[86:89], v[158:161], v[210:213], v[86:89]
	v_mfma_f32_16x16x32_bf16 v[78:81], v[150:153], v[228:231], v[78:81]
	v_mfma_f32_16x16x32_bf16 v[70:73], v[158:161], v[228:231], v[70:73]
	v_mfma_f32_16x16x32_bf16 v[126:129], v[154:157], v[198:201], v[126:129]
	v_mfma_f32_16x16x32_bf16 v[118:121], v[180:183], v[198:201], v[118:121]
	v_mfma_f32_16x16x32_bf16 v[110:113], v[154:157], v[206:209], v[110:113]
	v_mfma_f32_16x16x32_bf16 v[102:105], v[180:183], v[206:209], v[102:105]
	v_mfma_f32_16x16x32_bf16 v[94:97], v[154:157], v[224:227], v[94:97]
	v_mfma_f32_16x16x32_bf16 v[86:89], v[180:183], v[224:227], v[86:89]
	v_mfma_f32_16x16x32_bf16 v[78:81], v[154:157], v[232:235], v[78:81]
	v_mfma_f32_16x16x32_bf16 v[70:73], v[180:183], v[232:235], v[70:73]
	s_setprio 0
	s_barrier
	ds_read_b128 v[184:187], v178 offset:16384
	ds_read_b128 v[198:201], v178 offset:17408
	ds_read_b128 v[202:205], v178 offset:18432
	ds_read_b128 v[206:209], v178 offset:19456
	ds_read_b128 v[210:213], v178 offset:20480
	ds_read_b128 v[224:227], v178 offset:21504
	ds_read_b128 v[228:231], v178 offset:22528
	ds_read_b128 v[232:235], v178 offset:23552
	s_mov_b32 m0, s52
	s_nop 0
	global_load_lds_dwordx4 v166, s[34:35]
	s_mov_b32 m0, s58
	s_nop 0
	global_load_lds_dwordx4 v162, s[34:35]
	s_add_u32 vcc_lo, s34, 0x40000
	s_addc_u32 vcc_hi, s35, 0
	s_mov_b32 m0, s59
	s_nop 0
	global_load_lds_dwordx4 v166, vcc
	s_mov_b32 m0, s62
	s_nop 0
	global_load_lds_dwordx4 v162, vcc
	s_mov_b32 m0, s7
	s_nop 0
	global_load_lds_dwordx4 v168, s[48:49]
	s_mov_b32 m0, s63
	s_nop 0
	global_load_lds_dwordx4 v164, s[48:49]
	s_waitcnt vmcnt(8)
	s_waitcnt lgkmcnt(0)
	s_barrier
	s_setprio 1
	v_mfma_f32_16x16x32_bf16 v[58:61], v[134:137], v[184:187], v[58:61]
	v_mfma_f32_16x16x32_bf16 v[50:53], v[142:145], v[184:187], v[50:53]
	v_mfma_f32_16x16x32_bf16 v[42:45], v[134:137], v[202:205], v[42:45]
	v_mfma_f32_16x16x32_bf16 v[34:37], v[142:145], v[202:205], v[34:37]
	v_mfma_f32_16x16x32_bf16 v[26:29], v[134:137], v[210:213], v[26:29]
	v_mfma_f32_16x16x32_bf16 v[18:21], v[142:145], v[210:213], v[18:21]
	v_mfma_f32_16x16x32_bf16 v[10:13], v[134:137], v[228:231], v[10:13]
	v_mfma_f32_16x16x32_bf16 v[2:5], v[142:145], v[228:231], v[2:5]
	v_mfma_f32_16x16x32_bf16 v[58:61], v[138:141], v[198:201], v[58:61]
	v_mfma_f32_16x16x32_bf16 v[50:53], v[146:149], v[198:201], v[50:53]
	v_mfma_f32_16x16x32_bf16 v[42:45], v[138:141], v[206:209], v[42:45]
	v_mfma_f32_16x16x32_bf16 v[34:37], v[146:149], v[206:209], v[34:37]
	v_mfma_f32_16x16x32_bf16 v[26:29], v[138:141], v[224:227], v[26:29]
	v_mfma_f32_16x16x32_bf16 v[18:21], v[146:149], v[224:227], v[18:21]
	v_mfma_f32_16x16x32_bf16 v[10:13], v[138:141], v[232:235], v[10:13]
	v_mfma_f32_16x16x32_bf16 v[2:5], v[146:149], v[232:235], v[2:5]
	s_setprio 0
	s_setprio 1
	v_mfma_f32_16x16x32_bf16 v[62:65], v[150:153], v[184:187], v[62:65]
	v_mfma_f32_16x16x32_bf16 v[54:57], v[158:161], v[184:187], v[54:57]
	v_mfma_f32_16x16x32_bf16 v[46:49], v[150:153], v[202:205], v[46:49]
	v_mfma_f32_16x16x32_bf16 v[38:41], v[158:161], v[202:205], v[38:41]
	v_mfma_f32_16x16x32_bf16 v[30:33], v[150:153], v[210:213], v[30:33]
	v_mfma_f32_16x16x32_bf16 v[22:25], v[158:161], v[210:213], v[22:25]
	v_mfma_f32_16x16x32_bf16 v[14:17], v[150:153], v[228:231], v[14:17]
	v_mfma_f32_16x16x32_bf16 v[6:9], v[158:161], v[228:231], v[6:9]
	v_mfma_f32_16x16x32_bf16 v[62:65], v[154:157], v[198:201], v[62:65]
	v_mfma_f32_16x16x32_bf16 v[54:57], v[180:183], v[198:201], v[54:57]
	v_mfma_f32_16x16x32_bf16 v[46:49], v[154:157], v[206:209], v[46:49]
	v_mfma_f32_16x16x32_bf16 v[38:41], v[180:183], v[206:209], v[38:41]
	v_mfma_f32_16x16x32_bf16 v[30:33], v[154:157], v[224:227], v[30:33]
	v_mfma_f32_16x16x32_bf16 v[22:25], v[180:183], v[224:227], v[22:25]
	v_mfma_f32_16x16x32_bf16 v[14:17], v[154:157], v[232:235], v[14:17]
	v_mfma_f32_16x16x32_bf16 v[6:9], v[180:183], v[232:235], v[6:9]
	s_setprio 0
	s_barrier
; #define PG8_STAGE(bufoff, gbase, voff) do { _Pragma("unroll") for (int _i = 0; _i < 2; ++_i) \
;         glds16_asm((const char*)(gbase) + (voff)[_i], ldsb + (unsigned)((bufoff) + _i * 8192)); } while (0)
; #define PG8_LDA(dst, b, h) do { _Pragma("unroll") for (int m = 0; m < 4; ++m) _Pragma("unroll") for (int k = 0; k < 2; ++k) dst[m][k] = *(const PG8_LAS bf16x8*)(lds + PG8_SA(b, h) + aoff + m * 2048 + k * 1024); } while (0)
; #define PG8_LDB(dst, b, h) do { _Pragma("unroll") for (int n = 0; n < 2; ++n) _Pragma("unroll") for (int k = 0; k < 2; ++k) dst[n][k] = *(const PG8_LAS bf16x8*)(lds + PG8_SB(b, h) + boff + n * 2048 + k * 1024); } while (0)
; #define PG8_MMA(ai, bj, At, Bt) do { __builtin_amdgcn_s_setprio(1); _Pragma("unroll") for (int m = 0; m < 4; ++m) _Pragma("unroll") for (int n = 0; n < 2; ++n) _Pragma("unroll") for (int k = 0; k < 2; ++k) \
;         acc[ai][bj][m][n] = __builtin_amdgcn_mfma_f32_16x16x32_bf16(Bt[n][k], At[m][k], acc[ai][bj][m][n], 0, 0, 0); __builtin_amdgcn_s_setprio(0); } while (0)
; #define PG8_WAIT_V(n) asm volatile("s_waitcnt vmcnt(" #n ")" ::: "memory")
; #define PG8_WAIT_L(n) asm volatile("s_waitcnt lgkmcnt(" #n ")" ::: "memory")
; #define PG8_BAR __builtin_amdgcn_s_barrier()
; #define PG8_SCHED __builtin_amdgcn_sched_barrier(0)
; template <class Epi, class Sched, bool ALIGN_EPI = false, bool SP2 = false>
; __device__ __forceinline__ void gemm_phase(PG8_LAS unsigned char* lds, const Gemm g, const Sched& S, const Epi& E, int wave_u) {
;     ...
;         for (int t = 0; t < nt; t += 2) {
;     ...
;             PG8_LDB(B0, 1, 0); PG8_LDB(B1, 1, 1); PG8_SCHED; PG8_LDA(At, 1, 0); PG8_STAGE(PG8_SA(0, 1), a2 + hstep, voffA);
;             PG8_WAIT_V(8); PG8_WAIT_L(0); PG8_BAR; PG8_MMA(0, 0, At, B0); PG8_MMA(0, 1, At, B1); PG8_BAR; PG8_SCHED;
;             PG8_LDA(At, 1, 1); PG8_STAGE(PG8_SB(1, 0), b3, voffB); PG8_STAGE(PG8_SB(1, 1), b3 + hstep, voffB); PG8_STAGE(PG8_SA(1, 0), a3, voffA);
;             PG8_WAIT_V(8); PG8_WAIT_L(0); PG8_BAR; PG8_MMA(1, 0, At, B0); PG8_MMA(1, 1, At, B1); PG8_BAR; PG8_SCHED;
	v_add_u32_e32 v146, 0x18000, v177
	v_add_u32_e32 v179, 0x1c000, v177
	ds_read_b128 v[134:137], v146
	ds_read_b128 v[138:141], v146 offset:1024
	ds_read_b128 v[142:145], v146 offset:2048
	ds_read_b128 v[146:149], v146 offset:3072
	ds_read_b128 v[150:153], v179
	ds_read_b128 v[154:157], v179 offset:1024
	ds_read_b128 v[158:161], v179 offset:2048
	ds_read_b128 v[180:183], v179 offset:3072
	ds_read_b128 v[184:187], v178 offset:32768
	ds_read_b128 v[198:201], v178 offset:33792
	ds_read_b128 v[202:205], v178 offset:34816
	ds_read_b128 v[206:209], v178 offset:35840
	ds_read_b128 v[210:213], v178 offset:36864
	ds_read_b128 v[224:227], v178 offset:37888
	ds_read_b128 v[228:231], v178 offset:38912
	ds_read_b128 v[232:235], v178 offset:39936
	s_add_u32 s48, s48, 0x40000
	s_addc_u32 s49, s49, 0
	s_mov_b32 m0, s64
	s_nop 0
	global_load_lds_dwordx4 v168, s[48:49]
	s_mov_b32 m0, s65
	s_nop 0
	global_load_lds_dwordx4 v164, s[48:49]
	s_waitcnt vmcnt(8)
	s_waitcnt lgkmcnt(0)
	s_barrier
	s_setprio 1
	v_mfma_f32_16x16x32_bf16 v[122:125], v[134:137], v[184:187], v[122:125]
	v_mfma_f32_16x16x32_bf16 v[114:117], v[142:145], v[184:187], v[114:117]
	v_mfma_f32_16x16x32_bf16 v[106:109], v[134:137], v[202:205], v[106:109]
	v_mfma_f32_16x16x32_bf16 v[98:101], v[142:145], v[202:205], v[98:101]
	v_mfma_f32_16x16x32_bf16 v[90:93], v[134:137], v[210:213], v[90:93]
	v_mfma_f32_16x16x32_bf16 v[82:85], v[142:145], v[210:213], v[82:85]
	v_mfma_f32_16x16x32_bf16 v[74:77], v[134:137], v[228:231], v[74:77]
	v_mfma_f32_16x16x32_bf16 v[66:69], v[142:145], v[228:231], v[66:69]
	v_mfma_f32_16x16x32_bf16 v[122:125], v[138:141], v[198:201], v[122:125]
	v_mfma_f32_16x16x32_bf16 v[114:117], v[146:149], v[198:201], v[114:117]
	v_mfma_f32_16x16x32_bf16 v[106:109], v[138:141], v[206:209], v[106:109]
	v_mfma_f32_16x16x32_bf16 v[98:101], v[146:149], v[206:209], v[98:101]
	v_mfma_f32_16x16x32_bf16 v[90:93], v[138:141], v[224:227], v[90:93]
	v_mfma_f32_16x16x32_bf16 v[82:85], v[146:149], v[224:227], v[82:85]
	v_mfma_f32_16x16x32_bf16 v[74:77], v[138:141], v[232:235], v[74:77]
	v_mfma_f32_16x16x32_bf16 v[66:69], v[146:149], v[232:235], v[66:69]
	s_setprio 0
	s_setprio 1
	v_mfma_f32_16x16x32_bf16 v[126:129], v[150:153], v[184:187], v[126:129]
	v_mfma_f32_16x16x32_bf16 v[118:121], v[158:161], v[184:187], v[118:121]
	v_mfma_f32_16x16x32_bf16 v[110:113], v[150:153], v[202:205], v[110:113]
	v_mfma_f32_16x16x32_bf16 v[102:105], v[158:161], v[202:205], v[102:105]
	v_mfma_f32_16x16x32_bf16 v[94:97], v[150:153], v[210:213], v[94:97]
	v_mfma_f32_16x16x32_bf16 v[86:89], v[158:161], v[210:213], v[86:89]
	v_mfma_f32_16x16x32_bf16 v[78:81], v[150:153], v[228:231], v[78:81]
	v_mfma_f32_16x16x32_bf16 v[70:73], v[158:161], v[228:231], v[70:73]
	v_mfma_f32_16x16x32_bf16 v[126:129], v[154:157], v[198:201], v[126:129]
	v_mfma_f32_16x16x32_bf16 v[118:121], v[180:183], v[198:201], v[118:121]
	v_mfma_f32_16x16x32_bf16 v[110:113], v[154:157], v[206:209], v[110:113]
	v_mfma_f32_16x16x32_bf16 v[102:105], v[180:183], v[206:209], v[102:105]
	v_mfma_f32_16x16x32_bf16 v[94:97], v[154:157], v[224:227], v[94:97]
	v_mfma_f32_16x16x32_bf16 v[86:89], v[180:183], v[224:227], v[86:89]
	v_mfma_f32_16x16x32_bf16 v[78:81], v[154:157], v[232:235], v[78:81]
	v_mfma_f32_16x16x32_bf16 v[70:73], v[180:183], v[232:235], v[70:73]
	s_setprio 0
	s_barrier
	ds_read_b128 v[184:187], v178 offset:49152
	ds_read_b128 v[198:201], v178 offset:50176
	ds_read_b128 v[202:205], v178 offset:51200
	ds_read_b128 v[206:209], v178 offset:52224
	ds_read_b128 v[210:213], v178 offset:53248
	ds_read_b128 v[224:227], v178 offset:54272
	ds_read_b128 v[228:231], v178 offset:55296
	ds_read_b128 v[232:235], v178 offset:56320
	s_mov_b32 m0, s66
	s_nop 0
	global_load_lds_dwordx4 v166, s[46:47]
	s_add_u32 s34, s34, 0x40080
	s_mov_b32 m0, s67
	s_nop 0
	global_load_lds_dwordx4 v162, s[46:47]
	s_addc_u32 s35, s35, 0
	s_mov_b32 m0, s79
	s_nop 0
	global_load_lds_dwordx4 v166, s[34:35]
	s_mov_b32 m0, s86
	s_nop 0
	global_load_lds_dwordx4 v162, s[34:35]
	s_mov_b32 m0, s75
	s_nop 0
	global_load_lds_dwordx4 v168, s[44:45]
	s_mov_b32 m0, s78
	s_nop 0
	global_load_lds_dwordx4 v164, s[44:45]
	s_waitcnt vmcnt(8)
	s_waitcnt lgkmcnt(0)
	s_barrier
	s_setprio 1
	v_mfma_f32_16x16x32_bf16 v[58:61], v[134:137], v[184:187], v[58:61]
	v_mfma_f32_16x16x32_bf16 v[50:53], v[142:145], v[184:187], v[50:53]
	v_mfma_f32_16x16x32_bf16 v[42:45], v[134:137], v[202:205], v[42:45]
	v_mfma_f32_16x16x32_bf16 v[34:37], v[142:145], v[202:205], v[34:37]
	v_mfma_f32_16x16x32_bf16 v[26:29], v[134:137], v[210:213], v[26:29]
	v_mfma_f32_16x16x32_bf16 v[18:21], v[142:145], v[210:213], v[18:21]
	v_mfma_f32_16x16x32_bf16 v[10:13], v[134:137], v[228:231], v[10:13]
	v_mfma_f32_16x16x32_bf16 v[2:5], v[142:145], v[228:231], v[2:5]
	v_mfma_f32_16x16x32_bf16 v[58:61], v[138:141], v[198:201], v[58:61]
	v_mfma_f32_16x16x32_bf16 v[50:53], v[146:149], v[198:201], v[50:53]
	v_mfma_f32_16x16x32_bf16 v[42:45], v[138:141], v[206:209], v[42:45]
	v_mfma_f32_16x16x32_bf16 v[34:37], v[146:149], v[206:209], v[34:37]
	v_mfma_f32_16x16x32_bf16 v[26:29], v[138:141], v[224:227], v[26:29]
	v_mfma_f32_16x16x32_bf16 v[18:21], v[146:149], v[224:227], v[18:21]
	v_mfma_f32_16x16x32_bf16 v[10:13], v[138:141], v[232:235], v[10:13]
	v_mfma_f32_16x16x32_bf16 v[2:5], v[146:149], v[232:235], v[2:5]
	s_setprio 0
	s_setprio 1
	v_mfma_f32_16x16x32_bf16 v[62:65], v[150:153], v[184:187], v[62:65]
	v_mfma_f32_16x16x32_bf16 v[54:57], v[158:161], v[184:187], v[54:57]
	v_mfma_f32_16x16x32_bf16 v[46:49], v[150:153], v[202:205], v[46:49]
	v_mfma_f32_16x16x32_bf16 v[38:41], v[158:161], v[202:205], v[38:41]
	v_mfma_f32_16x16x32_bf16 v[30:33], v[150:153], v[210:213], v[30:33]
	v_mfma_f32_16x16x32_bf16 v[22:25], v[158:161], v[210:213], v[22:25]
	v_mfma_f32_16x16x32_bf16 v[14:17], v[150:153], v[228:231], v[14:17]
	v_mfma_f32_16x16x32_bf16 v[6:9], v[158:161], v[228:231], v[6:9]
	v_mfma_f32_16x16x32_bf16 v[62:65], v[154:157], v[198:201], v[62:65]
	v_mfma_f32_16x16x32_bf16 v[54:57], v[180:183], v[198:201], v[54:57]
	v_mfma_f32_16x16x32_bf16 v[46:49], v[154:157], v[206:209], v[46:49]
	v_mfma_f32_16x16x32_bf16 v[38:41], v[180:183], v[206:209], v[38:41]
	v_mfma_f32_16x16x32_bf16 v[30:33], v[154:157], v[224:227], v[30:33]
	v_mfma_f32_16x16x32_bf16 v[22:25], v[180:183], v[224:227], v[22:25]
	v_mfma_f32_16x16x32_bf16 v[14:17], v[154:157], v[232:235], v[14:17]
	v_mfma_f32_16x16x32_bf16 v[6:9], v[180:183], v[232:235], v[6:9]
	s_setprio 0
	s_barrier
	s_add_i32 s1, s1, 2
	s_add_u32 s60, s60, 0x100
	s_addc_u32 s61, s61, 0
	s_add_u32 s84, s84, 0x100
	s_addc_u32 s85, s85, 0
	s_cmp_gt_u32 s1, 13
	s_cbranch_scc1 .LBB0_1178

; #define PG8_STAGE(bufoff, gbase, voff) do { _Pragma("unroll") for (int _i = 0; _i < 2; ++_i) \
;         glds16_asm((const char*)(gbase) + (voff)[_i], ldsb + (unsigned)((bufoff) + _i * 8192)); } while (0)
; #define PG8_LDA(dst, b, h) do { _Pragma("unroll") for (int m = 0; m < 4; ++m) _Pragma("unroll") for (int k = 0; k < 2; ++k) dst[m][k] = *(const PG8_LAS bf16x8*)(lds + PG8_SA(b, h) + aoff + m * 2048 + k * 1024); } while (0)
; #define PG8_LDB(dst, b, h) do { _Pragma("unroll") for (int n = 0; n < 2; ++n) _Pragma("unroll") for (int k = 0; k < 2; ++k) dst[n][k] = *(const PG8_LAS bf16x8*)(lds + PG8_SB(b, h) + boff + n * 2048 + k * 1024); } while (0)
; #define PG8_MMA(ai, bj, At, Bt) do { __builtin_amdgcn_s_setprio(1); _Pragma("unroll") for (int m = 0; m < 4; ++m) _Pragma("unroll") for (int n = 0; n < 2; ++n) _Pragma("unroll") for (int k = 0; k < 2; ++k) \
;         acc[ai][bj][m][n] = __builtin_amdgcn_mfma_f32_16x16x32_bf16(Bt[n][k], At[m][k], acc[ai][bj][m][n], 0, 0, 0); __builtin_amdgcn_s_setprio(0); } while (0)
; #define PG8_WAIT_V(n) asm volatile("s_waitcnt vmcnt(" #n ")" ::: "memory")
; #define PG8_WAIT_L(n) asm volatile("s_waitcnt lgkmcnt(" #n ")" ::: "memory")
; #define PG8_BAR __builtin_amdgcn_s_barrier()
; #define PG8_SCHED __builtin_amdgcn_sched_barrier(0)
; template <class Epi, class Sched, bool ALIGN_EPI = false, bool SP2 = false>
; __device__ __forceinline__ void gemm_phase(PG8_LAS unsigned char* lds, const Gemm g, const Sched& S, const Epi& E, int wave_u) {
;     ...
;             PG8_LDB(B0, 0, 0); PG8_LDB(B1, 0, 1); PG8_SCHED; PG8_LDA(At, 0, 0); PG8_STAGE(PG8_SA(1, 1), a1 + hstep, voffA);
;             PG8_WAIT_V(8); PG8_WAIT_L(0); PG8_BAR; PG8_MMA(0, 0, At, B0); PG8_MMA(0, 1, At, B1); PG8_BAR; PG8_SCHED;
;             PG8_LDA(At, 0, 1); PG8_STAGE(PG8_SB(0, 0), b2, voffB); PG8_STAGE(PG8_SB(0, 1), b2 + hstep, voffB); PG8_STAGE(PG8_SA(0, 0), a2, voffA);
;             PG8_WAIT_V(8); PG8_WAIT_L(0); PG8_BAR; PG8_MMA(1, 0, At, B0); PG8_MMA(1, 1, At, B1); PG8_BAR; PG8_SCHED;
.LBB0_1428:
	v_add_u32_e32 v0, 0x10000, v227
	ds_read_b128 v[62:65], v0
	ds_read_b128 v[74:77], v0 offset:1024
	ds_read_b128 v[90:93], v0 offset:2048
	ds_read_b128 v[98:101], v0 offset:3072
	v_add_u32_e32 v0, 0x14000, v227
	s_add_u32 s46, s28, 0xfff50080
	ds_read_b128 v[114:117], v0
	ds_read_b128 v[122:125], v0 offset:1024
	ds_read_b128 v[138:141], v0 offset:2048
	ds_read_b128 v[146:149], v0 offset:3072
	s_addc_u32 s47, s29, -1
	s_and_b64 s[44:45], s[44:45], exec
	s_cselect_b32 s56, s22, s46
	s_cselect_b32 s57, s23, s47
	s_cselect_b32 s45, s25, s61
	s_cselect_b32 s44, s24, s60
	s_add_u32 s46, s56, 0x80
	s_addc_u32 s47, s57, 0
	s_add_u32 s48, s44, 0x80
	s_addc_u32 s49, s45, 0
	ds_read_b128 v[158:161], v228
	ds_read_b128 v[162:165], v228 offset:1024
	ds_read_b128 v[174:177], v228 offset:2048
	ds_read_b128 v[178:181], v228 offset:3072
	ds_read_b128 v[182:185], v228 offset:4096
	ds_read_b128 v[186:189], v228 offset:5120
	ds_read_b128 v[210:213], v228 offset:6144
	ds_read_b128 v[230:233], v228 offset:7168
	s_mov_b32 m0, s7
	s_nop 0
	global_load_lds_dwordx4 v198, s[28:29]
	s_mov_b32 m0, s75
	s_nop 0
	global_load_lds_dwordx4 v202, s[28:29]
	s_waitcnt vmcnt(8)
	s_waitcnt lgkmcnt(0)
	s_barrier
	s_setprio 1
	v_mfma_f32_16x16x32_bf16 v[170:173], v[62:65], v[158:161], v[170:173]
	v_mfma_f32_16x16x32_bf16 v[166:169], v[90:93], v[158:161], v[166:169]
	v_mfma_f32_16x16x32_bf16 v[142:145], v[62:65], v[174:177], v[142:145]
	v_mfma_f32_16x16x32_bf16 v[134:137], v[90:93], v[174:177], v[134:137]
	v_mfma_f32_16x16x32_bf16 v[118:121], v[62:65], v[182:185], v[118:121]
	v_mfma_f32_16x16x32_bf16 v[110:113], v[90:93], v[182:185], v[110:113]
	v_mfma_f32_16x16x32_bf16 v[94:97], v[62:65], v[210:213], v[94:97]
	v_mfma_f32_16x16x32_bf16 v[86:89], v[90:93], v[210:213], v[86:89]
	v_mfma_f32_16x16x32_bf16 v[170:173], v[74:77], v[162:165], v[170:173]
	v_mfma_f32_16x16x32_bf16 v[166:169], v[98:101], v[162:165], v[166:169]
	v_mfma_f32_16x16x32_bf16 v[142:145], v[74:77], v[178:181], v[142:145]
	v_mfma_f32_16x16x32_bf16 v[134:137], v[98:101], v[178:181], v[134:137]
	v_mfma_f32_16x16x32_bf16 v[118:121], v[74:77], v[186:189], v[118:121]
	v_mfma_f32_16x16x32_bf16 v[110:113], v[98:101], v[186:189], v[110:113]
	v_mfma_f32_16x16x32_bf16 v[94:97], v[74:77], v[230:233], v[94:97]
	v_mfma_f32_16x16x32_bf16 v[86:89], v[98:101], v[230:233], v[86:89]
	s_setprio 0
	s_setprio 1
	v_mfma_f32_16x16x32_bf16 v[154:157], v[114:117], v[158:161], v[154:157]
	v_mfma_f32_16x16x32_bf16 v[150:153], v[138:141], v[158:161], v[150:153]
	v_mfma_f32_16x16x32_bf16 v[130:133], v[114:117], v[174:177], v[130:133]
	v_mfma_f32_16x16x32_bf16 v[126:129], v[138:141], v[174:177], v[126:129]
	v_mfma_f32_16x16x32_bf16 v[106:109], v[114:117], v[182:185], v[106:109]
	v_mfma_f32_16x16x32_bf16 v[102:105], v[138:141], v[182:185], v[102:105]
	v_mfma_f32_16x16x32_bf16 v[82:85], v[114:117], v[210:213], v[82:85]
	v_mfma_f32_16x16x32_bf16 v[78:81], v[138:141], v[210:213], v[78:81]
	v_mfma_f32_16x16x32_bf16 v[154:157], v[122:125], v[162:165], v[154:157]
	v_mfma_f32_16x16x32_bf16 v[150:153], v[146:149], v[162:165], v[150:153]
	v_mfma_f32_16x16x32_bf16 v[130:133], v[122:125], v[178:181], v[130:133]
	v_mfma_f32_16x16x32_bf16 v[126:129], v[146:149], v[178:181], v[126:129]
	v_mfma_f32_16x16x32_bf16 v[106:109], v[122:125], v[186:189], v[106:109]
	v_mfma_f32_16x16x32_bf16 v[102:105], v[146:149], v[186:189], v[102:105]
	v_mfma_f32_16x16x32_bf16 v[82:85], v[122:125], v[230:233], v[82:85]
	v_mfma_f32_16x16x32_bf16 v[78:81], v[146:149], v[230:233], v[78:81]
	s_setprio 0
	s_barrier
	ds_read_b128 v[158:161], v228 offset:16384
	ds_read_b128 v[162:165], v228 offset:17408
	ds_read_b128 v[174:177], v228 offset:18432
	ds_read_b128 v[178:181], v228 offset:19456
	ds_read_b128 v[182:185], v228 offset:20480
	ds_read_b128 v[186:189], v228 offset:21504
	ds_read_b128 v[210:213], v228 offset:22528
	ds_read_b128 v[230:233], v228 offset:23552
	s_mov_b32 m0, s27
	s_nop 0
	global_load_lds_dwordx4 v200, s[44:45]
	s_mov_b32 m0, s86
	s_nop 0
	global_load_lds_dwordx4 v204, s[44:45]
	s_add_u32 s64, s44, 0xb0000
	s_addc_u32 s65, s45, 0
	s_mov_b32 m0, s87
	s_nop 0
	global_load_lds_dwordx4 v200, s[64:65]
	s_mov_b32 m0, s88
	s_nop 0
	global_load_lds_dwordx4 v204, s[64:65]
	s_mov_b32 m0, s84
	s_nop 0
	global_load_lds_dwordx4 v198, s[56:57]
	s_mov_b32 m0, s89
	s_nop 0
	global_load_lds_dwordx4 v202, s[56:57]
	s_waitcnt vmcnt(8)
	s_waitcnt lgkmcnt(0)
	s_barrier
	s_setprio 1
	v_mfma_f32_16x16x32_bf16 v[70:73], v[62:65], v[158:161], v[70:73]
	v_mfma_f32_16x16x32_bf16 v[66:69], v[90:93], v[158:161], v[66:69]
	v_mfma_f32_16x16x32_bf16 v[46:49], v[62:65], v[174:177], v[46:49]
	v_mfma_f32_16x16x32_bf16 v[42:45], v[90:93], v[174:177], v[42:45]
	v_mfma_f32_16x16x32_bf16 v[30:33], v[62:65], v[182:185], v[30:33]
	v_mfma_f32_16x16x32_bf16 v[26:29], v[90:93], v[182:185], v[26:29]
	v_mfma_f32_16x16x32_bf16 v[14:17], v[62:65], v[210:213], v[14:17]
	v_mfma_f32_16x16x32_bf16 v[10:13], v[90:93], v[210:213], v[10:13]
	v_mfma_f32_16x16x32_bf16 v[70:73], v[74:77], v[162:165], v[70:73]
	v_mfma_f32_16x16x32_bf16 v[66:69], v[98:101], v[162:165], v[66:69]
	v_mfma_f32_16x16x32_bf16 v[46:49], v[74:77], v[178:181], v[46:49]
	v_mfma_f32_16x16x32_bf16 v[42:45], v[98:101], v[178:181], v[42:45]
	v_mfma_f32_16x16x32_bf16 v[30:33], v[74:77], v[186:189], v[30:33]
	v_mfma_f32_16x16x32_bf16 v[26:29], v[98:101], v[186:189], v[26:29]
	v_mfma_f32_16x16x32_bf16 v[14:17], v[74:77], v[230:233], v[14:17]
	v_mfma_f32_16x16x32_bf16 v[10:13], v[98:101], v[230:233], v[10:13]
	s_setprio 0
	s_setprio 1
	v_mfma_f32_16x16x32_bf16 v[58:61], v[114:117], v[158:161], v[58:61]
	v_mfma_f32_16x16x32_bf16 v[54:57], v[138:141], v[158:161], v[54:57]
	v_mfma_f32_16x16x32_bf16 v[38:41], v[114:117], v[174:177], v[38:41]
	v_mfma_f32_16x16x32_bf16 v[34:37], v[138:141], v[174:177], v[34:37]
	v_mfma_f32_16x16x32_bf16 v[22:25], v[114:117], v[182:185], v[22:25]
	v_mfma_f32_16x16x32_bf16 v[18:21], v[138:141], v[182:185], v[18:21]
	v_mfma_f32_16x16x32_bf16 v[6:9], v[114:117], v[210:213], v[6:9]
	v_mfma_f32_16x16x32_bf16 v[2:5], v[138:141], v[210:213], v[2:5]
	v_mfma_f32_16x16x32_bf16 v[58:61], v[122:125], v[162:165], v[58:61]
	v_mfma_f32_16x16x32_bf16 v[54:57], v[146:149], v[162:165], v[54:57]
	v_mfma_f32_16x16x32_bf16 v[38:41], v[122:125], v[178:181], v[38:41]
	v_mfma_f32_16x16x32_bf16 v[34:37], v[146:149], v[178:181], v[34:37]
	v_mfma_f32_16x16x32_bf16 v[22:25], v[122:125], v[186:189], v[22:25]
	v_mfma_f32_16x16x32_bf16 v[18:21], v[146:149], v[186:189], v[18:21]
	v_mfma_f32_16x16x32_bf16 v[6:9], v[122:125], v[230:233], v[6:9]
	v_mfma_f32_16x16x32_bf16 v[2:5], v[146:149], v[230:233], v[2:5]
	s_setprio 0
	s_barrier
; #define PG8_STAGE(bufoff, gbase, voff) do { _Pragma("unroll") for (int _i = 0; _i < 2; ++_i) \
;         glds16_asm((const char*)(gbase) + (voff)[_i], ldsb + (unsigned)((bufoff) + _i * 8192)); } while (0)
; #define PG8_LDA(dst, b, h) do { _Pragma("unroll") for (int m = 0; m < 4; ++m) _Pragma("unroll") for (int k = 0; k < 2; ++k) dst[m][k] = *(const PG8_LAS bf16x8*)(lds + PG8_SA(b, h) + aoff + m * 2048 + k * 1024); } while (0)
; #define PG8_WAIT_V(n) asm volatile("s_waitcnt vmcnt(" #n ")" ::: "memory")
; #define PG8_WAIT_L(n) asm volatile("s_waitcnt lgkmcnt(" #n ")" ::: "memory")
; template <class Epi, class Sched, bool ALIGN_EPI = false, bool SP2 = false>
; __device__ __forceinline__ void gemm_phase(PG8_LAS unsigned char* lds, const Gemm g, const Sched& S, const Epi& E, int wave_u) {
;     ...
;         for (int t = 0; t < nt; t += 2) {
;             const bool last = (t == nt - 2);
;             const char* a1 = cA + (size_t)(t + 1) * kstep;
;             const char* a2 = last ? nA : cA + (size_t)(t + 2) * kstep; const char* b2 = last ? nB : cB + (size_t)(t + 2) * kstep;
;             const char* a3 = a2 + kstep; const char* b3 = b2 + kstep;
;             if (last && has_next) { S.a_ready(nxt); epi_prefetch(E, nxt.pm, nxt.pn, evb + (unsigned)(((ui + 1) & 1) * EPV_BYTES), tid); }
;             if constexpr (SP2) {
;             PG8_LDB(B0, 0, 0); PG8_LDB(B1, 0, 1); PG8_SCHED; PG8_LDA(At, 0, 0); PG8_STAGE(PG8_SA(1, 1), a1 + hstep, voffA);
;             PG8_WAIT_V(8); PG8_WAIT_L(0); PG8_BAR; PG8_MMA(0, 0, At, B0); PG8_MMA(0, 1, At, B1); PG8_BAR; PG8_SCHED;
;             PG8_LDA(At, 0, 1); PG8_STAGE(PG8_SB(0, 0), b2, voffB); PG8_STAGE(PG8_SB(0, 1), b2 + hstep, voffB); PG8_STAGE(PG8_SA(0, 0), a2, voffA);
;             PG8_WAIT_V(8); PG8_WAIT_L(0); PG8_BAR; PG8_MMA(1, 0, At, B0); PG8_MMA(1, 1, At, B1); PG8_BAR; PG8_SCHED;
;             PG8_LDB(B0, 1, 0); PG8_LDB(B1, 1, 1); PG8_SCHED; PG8_LDA(At, 1, 0); PG8_STAGE(PG8_SA(0, 1), a2 + hstep, voffA);
;             PG8_WAIT_V(8); PG8_WAIT_L(0); PG8_BAR; PG8_MMA(0, 0, At, B0); PG8_MMA(0, 1, At, B1); PG8_BAR; PG8_SCHED;
;             PG8_LDA(At, 1, 1); PG8_STAGE(PG8_SB(1, 0), b3, voffB); PG8_STAGE(PG8_SB(1, 1), b3 + hstep, voffB); PG8_STAGE(PG8_SA(1, 0), a3, voffA);
;             PG8_WAIT_V(8); PG8_WAIT_L(0); PG8_BAR; PG8_MMA(1, 0, At, B0); PG8_MMA(1, 1, At, B1); PG8_BAR; PG8_SCHED;
	v_add_u32_e32 v0, 0x18000, v227
	ds_read_b128 v[62:65], v0
	ds_read_b128 v[74:77], v0 offset:1024
	ds_read_b128 v[90:93], v0 offset:2048
	ds_read_b128 v[98:101], v0 offset:3072
	v_add_u32_e32 v0, 0x1c000, v227
	ds_read_b128 v[114:117], v0
	ds_read_b128 v[122:125], v0 offset:1024
	ds_read_b128 v[138:141], v0 offset:2048
	ds_read_b128 v[146:149], v0 offset:3072
	ds_read_b128 v[158:161], v228 offset:32768
	ds_read_b128 v[162:165], v228 offset:33792
	ds_read_b128 v[174:177], v228 offset:34816
	ds_read_b128 v[178:181], v228 offset:35840
	ds_read_b128 v[182:185], v228 offset:36864
	ds_read_b128 v[186:189], v228 offset:37888
	ds_read_b128 v[210:213], v228 offset:38912
	ds_read_b128 v[230:233], v228 offset:39936
	s_add_u32 s56, s56, 0xb0000
	s_addc_u32 s57, s57, 0
	s_mov_b32 m0, s90
	s_nop 0
	global_load_lds_dwordx4 v198, s[56:57]
	s_mov_b32 m0, s91
	s_nop 0
	global_load_lds_dwordx4 v202, s[56:57]
	s_waitcnt vmcnt(8)
	s_waitcnt lgkmcnt(0)
	s_barrier
	s_setprio 1
	v_mfma_f32_16x16x32_bf16 v[170:173], v[62:65], v[158:161], v[170:173]
	v_mfma_f32_16x16x32_bf16 v[166:169], v[90:93], v[158:161], v[166:169]
	v_mfma_f32_16x16x32_bf16 v[142:145], v[62:65], v[174:177], v[142:145]
	v_mfma_f32_16x16x32_bf16 v[134:137], v[90:93], v[174:177], v[134:137]
	v_mfma_f32_16x16x32_bf16 v[118:121], v[62:65], v[182:185], v[118:121]
	v_mfma_f32_16x16x32_bf16 v[110:113], v[90:93], v[182:185], v[110:113]
	v_mfma_f32_16x16x32_bf16 v[94:97], v[62:65], v[210:213], v[94:97]
	v_mfma_f32_16x16x32_bf16 v[86:89], v[90:93], v[210:213], v[86:89]
	v_mfma_f32_16x16x32_bf16 v[170:173], v[74:77], v[162:165], v[170:173]
	v_mfma_f32_16x16x32_bf16 v[166:169], v[98:101], v[162:165], v[166:169]
	v_mfma_f32_16x16x32_bf16 v[142:145], v[74:77], v[178:181], v[142:145]
	v_mfma_f32_16x16x32_bf16 v[134:137], v[98:101], v[178:181], v[134:137]
	v_mfma_f32_16x16x32_bf16 v[118:121], v[74:77], v[186:189], v[118:121]
	v_mfma_f32_16x16x32_bf16 v[110:113], v[98:101], v[186:189], v[110:113]
	v_mfma_f32_16x16x32_bf16 v[94:97], v[74:77], v[230:233], v[94:97]
	v_mfma_f32_16x16x32_bf16 v[86:89], v[98:101], v[230:233], v[86:89]
	s_setprio 0
	s_setprio 1
	v_mfma_f32_16x16x32_bf16 v[154:157], v[114:117], v[158:161], v[154:157]
	v_mfma_f32_16x16x32_bf16 v[150:153], v[138:141], v[158:161], v[150:153]
	v_mfma_f32_16x16x32_bf16 v[130:133], v[114:117], v[174:177], v[130:133]
	v_mfma_f32_16x16x32_bf16 v[126:129], v[138:141], v[174:177], v[126:129]
	v_mfma_f32_16x16x32_bf16 v[106:109], v[114:117], v[182:185], v[106:109]
	v_mfma_f32_16x16x32_bf16 v[102:105], v[138:141], v[182:185], v[102:105]
	v_mfma_f32_16x16x32_bf16 v[82:85], v[114:117], v[210:213], v[82:85]
	v_mfma_f32_16x16x32_bf16 v[78:81], v[138:141], v[210:213], v[78:81]
	v_mfma_f32_16x16x32_bf16 v[154:157], v[122:125], v[162:165], v[154:157]
	v_mfma_f32_16x16x32_bf16 v[150:153], v[146:149], v[162:165], v[150:153]
	v_mfma_f32_16x16x32_bf16 v[130:133], v[122:125], v[178:181], v[130:133]
	v_mfma_f32_16x16x32_bf16 v[126:129], v[146:149], v[178:181], v[126:129]
	v_mfma_f32_16x16x32_bf16 v[106:109], v[122:125], v[186:189], v[106:109]
	v_mfma_f32_16x16x32_bf16 v[102:105], v[146:149], v[186:189], v[102:105]
	v_mfma_f32_16x16x32_bf16 v[82:85], v[122:125], v[230:233], v[82:85]
	v_mfma_f32_16x16x32_bf16 v[78:81], v[146:149], v[230:233], v[78:81]
	s_setprio 0
	s_barrier
	ds_read_b128 v[158:161], v228 offset:49152
	ds_read_b128 v[162:165], v228 offset:50176
	ds_read_b128 v[174:177], v228 offset:51200
	ds_read_b128 v[178:181], v228 offset:52224
	ds_read_b128 v[182:185], v228 offset:53248
	ds_read_b128 v[186:189], v228 offset:54272
	ds_read_b128 v[210:213], v228 offset:55296
	ds_read_b128 v[230:233], v228 offset:56320
	s_mov_b32 m0, s62
	s_nop 0
	global_load_lds_dwordx4 v200, s[48:49]
	s_add_u32 s44, s44, 0xb0080
	s_mov_b32 m0, s63
	s_nop 0
	global_load_lds_dwordx4 v204, s[48:49]
	s_addc_u32 s45, s45, 0
	s_mov_b32 m0, s66
	s_nop 0
	global_load_lds_dwordx4 v200, s[44:45]
	s_mov_b32 m0, s67
	s_nop 0
	global_load_lds_dwordx4 v204, s[44:45]
	s_mov_b32 m0, s40
	s_nop 0
	global_load_lds_dwordx4 v198, s[46:47]
	s_mov_b32 m0, s41
	s_nop 0
	global_load_lds_dwordx4 v202, s[46:47]
	s_waitcnt vmcnt(8)
	s_waitcnt lgkmcnt(0)
	s_barrier
	s_setprio 1
	v_mfma_f32_16x16x32_bf16 v[70:73], v[62:65], v[158:161], v[70:73]
	v_mfma_f32_16x16x32_bf16 v[66:69], v[90:93], v[158:161], v[66:69]
	v_mfma_f32_16x16x32_bf16 v[46:49], v[62:65], v[174:177], v[46:49]
	v_mfma_f32_16x16x32_bf16 v[42:45], v[90:93], v[174:177], v[42:45]
	v_mfma_f32_16x16x32_bf16 v[30:33], v[62:65], v[182:185], v[30:33]
	v_mfma_f32_16x16x32_bf16 v[26:29], v[90:93], v[182:185], v[26:29]
	v_mfma_f32_16x16x32_bf16 v[14:17], v[62:65], v[210:213], v[14:17]
	v_mfma_f32_16x16x32_bf16 v[10:13], v[90:93], v[210:213], v[10:13]
	v_mfma_f32_16x16x32_bf16 v[70:73], v[74:77], v[162:165], v[70:73]
	v_mfma_f32_16x16x32_bf16 v[66:69], v[98:101], v[162:165], v[66:69]
	v_mfma_f32_16x16x32_bf16 v[46:49], v[74:77], v[178:181], v[46:49]
	v_mfma_f32_16x16x32_bf16 v[42:45], v[98:101], v[178:181], v[42:45]
	v_mfma_f32_16x16x32_bf16 v[30:33], v[74:77], v[186:189], v[30:33]
	v_mfma_f32_16x16x32_bf16 v[26:29], v[98:101], v[186:189], v[26:29]
	v_mfma_f32_16x16x32_bf16 v[14:17], v[74:77], v[230:233], v[14:17]
	v_mfma_f32_16x16x32_bf16 v[10:13], v[98:101], v[230:233], v[10:13]
	s_setprio 0
	s_setprio 1
	v_mfma_f32_16x16x32_bf16 v[58:61], v[114:117], v[158:161], v[58:61]
	v_mfma_f32_16x16x32_bf16 v[54:57], v[138:141], v[158:161], v[54:57]
	v_mfma_f32_16x16x32_bf16 v[38:41], v[114:117], v[174:177], v[38:41]
	v_mfma_f32_16x16x32_bf16 v[34:37], v[138:141], v[174:177], v[34:37]
	v_mfma_f32_16x16x32_bf16 v[22:25], v[114:117], v[182:185], v[22:25]
	v_mfma_f32_16x16x32_bf16 v[18:21], v[138:141], v[182:185], v[18:21]
	v_mfma_f32_16x16x32_bf16 v[6:9], v[114:117], v[210:213], v[6:9]
	v_mfma_f32_16x16x32_bf16 v[2:5], v[138:141], v[210:213], v[2:5]
	v_mfma_f32_16x16x32_bf16 v[58:61], v[122:125], v[162:165], v[58:61]
	v_mfma_f32_16x16x32_bf16 v[54:57], v[146:149], v[162:165], v[54:57]
	v_mfma_f32_16x16x32_bf16 v[38:41], v[122:125], v[178:181], v[38:41]
	v_mfma_f32_16x16x32_bf16 v[34:37], v[146:149], v[178:181], v[34:37]
	v_mfma_f32_16x16x32_bf16 v[22:25], v[122:125], v[186:189], v[22:25]
	v_mfma_f32_16x16x32_bf16 v[18:21], v[146:149], v[186:189], v[18:21]
	v_mfma_f32_16x16x32_bf16 v[6:9], v[122:125], v[230:233], v[6:9]
	v_mfma_f32_16x16x32_bf16 v[2:5], v[146:149], v[230:233], v[2:5]
	s_setprio 0
	s_barrier
	s_add_i32 s1, s1, 2
	s_add_u32 s28, s28, 0x100
	s_addc_u32 s29, s29, 0
	s_add_u32 s60, s60, 0x100
	s_addc_u32 s61, s61, 0
	s_cmp_gt_u32 s1, 41
	s_cbranch_scc1 .LBB0_1431
